# PEER top-k keys kept as f32 bit patterns ordered with f32 max/min (no u32-sortable conversion in F, no inverse in G1)
# speedup vs baseline: 1.0050x; 1.0050x over previous
.LBB0_865:
	v_mov_b32_e32 v128, v176
	s_waitcnt vmcnt(0)
	s_barrier
	v_mov_b32_e32 v137, v176
	v_and_b32_e32 v130, 15, v128
	v_lshrrev_b32_e32 v131, 1, v128
	v_and_or_b32 v130, v131, s81, v130
	v_ashrrev_i32_e32 v131, 2, v128
	v_lshrrev_b32_e32 v128, 2, v128
	v_and_b32_e32 v128, 12, v128
	v_and_or_b32 v128, v131, s82, v128
	v_cvt_pk_bf16_f32 v60, v60, v61
	v_cvt_pk_bf16_f32 v61, v62, v63
	v_cvt_pk_bf16_f32 v52, v52, v53
	v_cvt_pk_bf16_f32 v53, v54, v55
	v_cvt_pk_bf16_f32 v56, v56, v57
	v_cvt_pk_bf16_f32 v57, v58, v59
	v_cvt_pk_bf16_f32 v48, v48, v49
	v_cvt_pk_bf16_f32 v49, v50, v51
	v_cvt_pk_bf16_f32 v44, v44, v45
	v_cvt_pk_bf16_f32 v45, v46, v47
	v_cvt_pk_bf16_f32 v32, v32, v33
	v_cvt_pk_bf16_f32 v33, v34, v35
	v_cvt_pk_bf16_f32 v36, v36, v37
	v_cvt_pk_bf16_f32 v37, v38, v39
	v_cvt_pk_bf16_f32 v24, v24, v25
	v_cvt_pk_bf16_f32 v25, v26, v27
	v_cvt_pk_bf16_f32 v40, v40, v41
	v_cvt_pk_bf16_f32 v41, v42, v43
	v_cvt_pk_bf16_f32 v28, v28, v29
	v_cvt_pk_bf16_f32 v29, v30, v31
	v_cvt_pk_bf16_f32 v20, v20, v21
	v_cvt_pk_bf16_f32 v21, v22, v23
	v_cvt_pk_bf16_f32 v16, v16, v17
	v_cvt_pk_bf16_f32 v17, v18, v19
	v_cvt_pk_bf16_f32 v12, v12, v13
	v_cvt_pk_bf16_f32 v13, v14, v15
	v_cvt_pk_bf16_f32 v8, v8, v9
	v_cvt_pk_bf16_f32 v9, v10, v11
	v_cvt_pk_bf16_f32 v4, v4, v5
	v_cvt_pk_bf16_f32 v5, v6, v7
	v_cvt_pk_bf16_f32 v0, v0, v1
	v_cvt_pk_bf16_f32 v1, v2, v3
	v_mul_u32_u24_e32 v62, 0x110, v130
	v_lshl_add_u32 v62, v128, 1, v62
	v_add_u32_e32 v54, 0x8000, v62
	ds_write2_b64 v54, v[60:61], v[52:53] offset1:4
	v_add_u32_e32 v50, 0x9000, v62
	ds_write2_b64 v50, v[56:57], v[48:49] offset0:32 offset1:36
	ds_write2_b64 v54, v[44:45], v[32:33] offset0:8 offset1:12
	ds_write2_b64 v50, v[36:37], v[24:25] offset0:40 offset1:44
	v_add_u32_e32 v26, 0x1a000, v62
	ds_write_b64 v26, v[40:41]
	ds_write_b64 v26, v[28:29] offset:4352
	v_add_u32_e32 v22, 0x1a020, v62
	ds_write_b64 v22, v[20:21]
	ds_write_b64 v22, v[16:17] offset:4352
	v_add_u32_e32 v14, 0x1a040, v62
	ds_write_b64 v14, v[12:13]
	ds_write_b64 v14, v[8:9] offset:4352
	v_add_u32_e32 v6, 0x1a060, v62
	ds_write_b64 v6, v[4:5]
	s_lshl_b32 s59, s87, 1
	ds_write_b64 v6, v[0:1] offset:4352
	s_nop 0
	v_ashrrev_i32_e32 v132, 8, v137
	v_add_u32_e32 v130, s59, v132
	v_bfe_u32 v135, v137, 7, 1
	v_ashrrev_i32_e32 v131, 31, v130
	v_and_b32_e32 v2, 31, v137
	v_lshlrev_b64 v[0:1], 7, v[130:131]
	v_lshlrev_b32_e32 v136, 6, v135
	v_or3_b32 v0, v0, v136, v2
	v_bfe_u32 v133, v137, 5, 1
	v_lshlrev_b64 v[0:1], 8, v[0:1]
	v_lshl_add_u64 v[0:1], s[4:5], 0, v[0:1]
	v_lshlrev_b32_e32 v128, 4, v133
	v_lshl_add_u64 v[8:9], v[0:1], 0, v[128:129]
	global_load_dwordx4 v[0:3], v[8:9], off
	v_add_co_u32_e32 v10, vcc, s76, v8
	v_mul_i32_i24_e32 v131, 0x12000, v132
	s_nop 0
	v_addc_co_u32_e32 v11, vcc, 0, v9, vcc
	global_load_dwordx4 v[4:7], v[10:11], off
	global_load_dwordx4 v[138:141], v[8:9], off offset:32
	global_load_dwordx4 v[142:145], v[10:11], off offset:32
	global_load_dwordx4 v[146:149], v[8:9], off offset:64
	global_load_dwordx4 v[150:153], v[8:9], off offset:96
	global_load_dwordx4 v[154:157], v[10:11], off offset:64
	global_load_dwordx4 v[158:161], v[10:11], off offset:96
	global_load_dwordx4 v[162:165], v[8:9], off offset:128
	global_load_dwordx4 v[166:169], v[8:9], off offset:160
	global_load_dwordx4 v[170:173], v[10:11], off offset:128
	global_load_dwordx4 v[178:181], v[10:11], off offset:160
	global_load_dwordx4 v[182:185], v[8:9], off offset:192
	global_load_dwordx4 v[186:189], v[8:9], off offset:224
	global_load_dwordx4 v[190:193], v[10:11], off offset:192
	global_load_dwordx4 v[194:197], v[10:11], off offset:224
	v_and_b32_e32 v8, 0x5f, v137
	v_mul_u32_u24_e32 v8, 0x110, v8
	v_add3_u32 v128, v131, v8, v128
	s_waitcnt lgkmcnt(0)
	s_barrier
	ds_read_b128 v[8:11], v128 offset:32768
	ds_read_b128 v[198:201], v128 offset:32800
	s_waitcnt vmcnt(15) lgkmcnt(1)
	v_mfma_f32_32x32x16_bf16 v[32:47], v[0:3], v[8:11], 0
	ds_read_b128 v[12:15], v128 offset:41472
	ds_read_b128 v[202:205], v128 offset:41504
	v_lshlrev_b32_e32 v135, 1, v135
	s_waitcnt vmcnt(14)
	v_mfma_f32_32x32x16_bf16 v[48:63], v[4:7], v[8:11], 0
	s_waitcnt lgkmcnt(1)
	v_mfma_f32_32x32x16_bf16 v[16:31], v[0:3], v[12:15], 0
	v_mfma_f32_32x32x16_bf16 v[0:15], v[4:7], v[12:15], 0
	s_waitcnt vmcnt(13)
	v_mfma_f32_32x32x16_bf16 v[32:47], v[138:141], v[198:201], v[32:47]
	s_waitcnt vmcnt(12)
	v_mfma_f32_32x32x16_bf16 v[48:63], v[142:145], v[198:201], v[48:63]
	s_waitcnt lgkmcnt(0)
	v_mfma_f32_32x32x16_bf16 v[16:31], v[138:141], v[202:205], v[16:31]
	v_mfma_f32_32x32x16_bf16 v[0:15], v[142:145], v[202:205], v[0:15]
	ds_read_b128 v[138:141], v128 offset:32832
	ds_read_b128 v[142:145], v128 offset:32864
	ds_read_b128 v[198:201], v128 offset:41536
	ds_read_b128 v[202:205], v128 offset:41568
	s_waitcnt vmcnt(11) lgkmcnt(3)
	v_mfma_f32_32x32x16_bf16 v[32:47], v[146:149], v[138:141], v[32:47]
	s_waitcnt vmcnt(9)
	v_mfma_f32_32x32x16_bf16 v[48:63], v[154:157], v[138:141], v[48:63]
	s_waitcnt lgkmcnt(1)
	v_mfma_f32_32x32x16_bf16 v[16:31], v[146:149], v[198:201], v[16:31]
	v_mfma_f32_32x32x16_bf16 v[0:15], v[154:157], v[198:201], v[0:15]
	v_mfma_f32_32x32x16_bf16 v[32:47], v[150:153], v[142:145], v[32:47]
	s_waitcnt vmcnt(8)
	v_mfma_f32_32x32x16_bf16 v[48:63], v[158:161], v[142:145], v[48:63]
	ds_read_b128 v[138:141], v128 offset:32896
	ds_read_b128 v[142:145], v128 offset:32928
	s_waitcnt lgkmcnt(2)
	v_mfma_f32_32x32x16_bf16 v[16:31], v[150:153], v[202:205], v[16:31]
	ds_read_b128 v[146:149], v128 offset:41600
	ds_read_b128 v[150:153], v128 offset:41632
	v_mfma_f32_32x32x16_bf16 v[0:15], v[158:161], v[202:205], v[0:15]
	s_waitcnt vmcnt(7) lgkmcnt(3)
	v_mfma_f32_32x32x16_bf16 v[32:47], v[162:165], v[138:141], v[32:47]
	s_waitcnt vmcnt(5)
	v_mfma_f32_32x32x16_bf16 v[48:63], v[170:173], v[138:141], v[48:63]
	s_waitcnt lgkmcnt(1)
	v_mfma_f32_32x32x16_bf16 v[16:31], v[162:165], v[146:149], v[16:31]
	v_mfma_f32_32x32x16_bf16 v[0:15], v[170:173], v[146:149], v[0:15]
	v_mfma_f32_32x32x16_bf16 v[32:47], v[166:169], v[142:145], v[32:47]
	s_waitcnt vmcnt(4)
	v_mfma_f32_32x32x16_bf16 v[48:63], v[178:181], v[142:145], v[48:63]
	ds_read_b128 v[138:141], v128 offset:32960
	ds_read_b128 v[142:145], v128 offset:32992
	s_waitcnt lgkmcnt(2)
	v_mfma_f32_32x32x16_bf16 v[16:31], v[166:169], v[150:153], v[16:31]
	v_mfma_f32_32x32x16_bf16 v[0:15], v[178:181], v[150:153], v[0:15]
	ds_read_b128 v[146:149], v128 offset:41664
	ds_read_b128 v[150:153], v128 offset:41696
	v_and_b32_e32 v128, 0xff, v137
	v_cmp_gt_u32_e32 vcc, s77, v128
	s_waitcnt vmcnt(3) lgkmcnt(3)
	v_mfma_f32_32x32x16_bf16 v[32:47], v[182:185], v[138:141], v[32:47]
	s_waitcnt vmcnt(1)
	v_mfma_f32_32x32x16_bf16 v[48:63], v[190:193], v[138:141], v[48:63]
	v_lshlrev_b32_e32 v138, 2, v133
	s_waitcnt lgkmcnt(1)
	v_mfma_f32_32x32x16_bf16 v[16:31], v[182:185], v[146:149], v[16:31]
	v_mfma_f32_32x32x16_bf16 v[0:15], v[190:193], v[146:149], v[0:15]
	v_mfma_f32_32x32x16_bf16 v[32:47], v[186:189], v[142:145], v[32:47]
	s_waitcnt vmcnt(0)
	v_mfma_f32_32x32x16_bf16 v[48:63], v[194:197], v[142:145], v[48:63]
	s_nop 9
	s_waitcnt lgkmcnt(0)
	v_mfma_f32_32x32x16_bf16 v[16:31], v[186:189], v[150:153], v[16:31]
	v_mfma_f32_32x32x16_bf16 v[0:15], v[194:197], v[150:153], v[0:15]
	v_and_b32_e32 v32, s86, v32
	v_and_b32_e32 v33, s86, v33
	v_and_b32_e32 v34, s86, v34
	v_and_b32_e32 v35, s86, v35
	v_and_b32_e32 v36, s86, v36
	v_and_b32_e32 v37, s86, v37
	v_and_b32_e32 v38, s86, v38
	v_and_b32_e32 v39, s86, v39
	v_and_b32_e32 v40, s86, v40
	v_and_b32_e32 v41, s86, v41
	v_and_b32_e32 v42, s86, v42
	v_and_b32_e32 v43, s86, v43
	v_and_b32_e32 v44, s86, v44
	v_and_b32_e32 v45, s86, v45
	v_and_b32_e32 v46, s86, v46
	v_and_b32_e32 v47, s86, v47
	v_or_b32_e32 v139, 1, v138
	v_or_b32_e32 v140, 2, v138
	v_or_b32_e32 v141, 3, v138
	v_or_b32_e32 v142, 8, v138
	v_or_b32_e32 v143, 9, v138
	v_or_b32_e32 v144, 10, v138
	v_or_b32_e32 v145, 11, v138
	v_or_b32_e32 v146, 16, v138
	v_or_b32_e32 v147, 17, v138
	v_or_b32_e32 v148, 18, v138
	v_or_b32_e32 v149, 19, v138
	v_or_b32_e32 v150, 24, v138
	v_or_b32_e32 v151, 25, v138
	v_or_b32_e32 v152, 26, v138
	v_or_b32_e32 v153, 27, v138
	v_and_or_b32 v48, v48, s86, v138
	v_and_or_b32 v49, v49, s86, v139
	v_and_or_b32 v50, v50, s86, v140
	v_and_or_b32 v51, v51, s86, v141
	v_and_or_b32 v52, v52, s86, v142
	v_and_or_b32 v53, v53, s86, v143
	v_and_or_b32 v54, v54, s86, v144
	v_and_or_b32 v55, v55, s86, v145
	v_and_or_b32 v56, v56, s86, v146
	v_and_or_b32 v57, v57, s86, v147
	v_and_or_b32 v58, v58, s86, v148
	v_and_or_b32 v59, v59, s86, v149
	v_and_or_b32 v60, v60, s86, v150
	v_and_or_b32 v61, v61, s86, v151
	v_and_or_b32 v62, v62, s86, v152
	v_and_or_b32 v63, v63, s86, v153
	v_or3_b32 v32, v136, v32, v138
	v_or3_b32 v48, v48, v136, 32
	v_or3_b32 v33, v136, v33, v139
	v_or3_b32 v49, v49, v136, 32
	v_or3_b32 v34, v136, v34, v140
	v_or3_b32 v50, v50, v136, 32
	v_or3_b32 v35, v136, v35, v141
	v_or3_b32 v51, v51, v136, 32
	v_or3_b32 v36, v136, v36, v142
	v_or3_b32 v52, v52, v136, 32
	v_or3_b32 v37, v136, v37, v143
	v_or3_b32 v53, v53, v136, 32
	v_or3_b32 v38, v136, v38, v144
	v_or3_b32 v54, v54, v136, 32
	v_or3_b32 v39, v136, v39, v145
	v_or3_b32 v55, v55, v136, 32
	v_or3_b32 v40, v136, v40, v146
	v_or3_b32 v56, v56, v136, 32
	v_or3_b32 v41, v136, v41, v147
	v_or3_b32 v57, v57, v136, 32
	v_or3_b32 v42, v136, v42, v148
	v_or3_b32 v58, v58, v136, 32
	v_or3_b32 v43, v136, v43, v149
	v_or3_b32 v59, v59, v136, 32
	v_or3_b32 v44, v136, v44, v150
	v_or3_b32 v60, v60, v136, 32
	v_or3_b32 v45, v136, v45, v151
	v_or3_b32 v61, v61, v136, 32
	v_or3_b32 v46, v136, v46, v152
	v_or3_b32 v62, v62, v136, 32
	v_or3_b32 v47, v136, v47, v153
	v_or3_b32 v63, v63, v136, 32
	v_max_f32_e32 v154, v32, v45
	v_min_f32_e32 v32, v32, v45
	v_max_f32_e32 v45, v33, v44
	v_min_f32_e32 v33, v33, v44
	v_max_f32_e32 v44, v34, v47
	v_min_f32_e32 v34, v34, v47
	v_max_f32_e32 v47, v35, v46
	v_min_f32_e32 v35, v35, v46
	v_max_f32_e32 v46, v36, v40
	v_min_f32_e32 v36, v36, v40
	v_max_f32_e32 v40, v37, v38
	v_min_f32_e32 v37, v37, v38
	v_max_f32_e32 v38, v39, v43
	v_min_f32_e32 v39, v39, v43
	v_max_f32_e32 v43, v41, v42
	v_min_f32_e32 v41, v41, v42
	v_max_f32_e32 v162, v48, v61
	v_min_f32_e32 v48, v48, v61
	v_max_f32_e32 v61, v49, v60
	v_min_f32_e32 v49, v49, v60
	v_max_f32_e32 v60, v50, v63
	v_min_f32_e32 v50, v50, v63
	v_max_f32_e32 v63, v51, v62
	v_min_f32_e32 v51, v51, v62
	v_max_f32_e32 v62, v52, v56
	v_min_f32_e32 v52, v52, v56
	v_max_f32_e32 v56, v53, v54
	v_min_f32_e32 v53, v53, v54
	v_max_f32_e32 v54, v55, v59
	v_min_f32_e32 v55, v55, v59
	v_max_f32_e32 v59, v57, v58
	v_min_f32_e32 v57, v57, v58
	v_max_f32_e32 v42, v154, v40
	v_min_f32_e32 v40, v154, v40
	v_max_f32_e32 v154, v45, v38
	v_min_f32_e32 v38, v45, v38
	v_max_f32_e32 v45, v44, v43
	v_min_f32_e32 v43, v44, v43
	v_max_f32_e32 v44, v47, v46
	v_min_f32_e32 v46, v47, v46
	v_max_f32_e32 v47, v37, v32
	v_min_f32_e32 v32, v37, v32
	v_max_f32_e32 v37, v36, v35
	v_min_f32_e32 v35, v36, v35
	v_max_f32_e32 v36, v41, v34
	v_min_f32_e32 v34, v41, v34
	v_max_f32_e32 v41, v39, v33
	v_min_f32_e32 v33, v39, v33
	v_max_f32_e32 v58, v162, v56
	v_min_f32_e32 v56, v162, v56
	v_max_f32_e32 v162, v61, v54
	v_min_f32_e32 v54, v61, v54
	v_max_f32_e32 v61, v60, v59
	v_min_f32_e32 v59, v60, v59
	v_max_f32_e32 v60, v63, v62
	v_min_f32_e32 v62, v63, v62
	v_max_f32_e32 v63, v53, v48
	v_min_f32_e32 v48, v53, v48
	v_max_f32_e32 v53, v52, v51
	v_min_f32_e32 v51, v52, v51
	v_max_f32_e32 v52, v57, v50
	v_min_f32_e32 v50, v57, v50
	v_max_f32_e32 v57, v55, v49
	v_min_f32_e32 v49, v55, v49
	v_max_f32_e32 v39, v42, v154
	v_min_f32_e32 v42, v42, v154
	v_max_f32_e32 v154, v45, v44
	v_min_f32_e32 v44, v45, v44
	v_max_f32_e32 v45, v46, v40
	v_min_f32_e32 v40, v46, v40
	v_max_f32_e32 v46, v47, v37
	v_min_f32_e32 v37, v47, v37
	v_max_f32_e32 v47, v38, v43
	v_min_f32_e32 v38, v38, v43
	v_max_f32_e32 v43, v36, v41
	v_min_f32_e32 v36, v36, v41
	v_max_f32_e32 v41, v33, v32
	v_min_f32_e32 v32, v33, v32
	v_max_f32_e32 v33, v35, v34
	v_min_f32_e32 v34, v35, v34
	v_max_f32_e32 v55, v58, v162
	v_min_f32_e32 v58, v58, v162
	v_max_f32_e32 v162, v61, v60
	v_min_f32_e32 v60, v61, v60
	v_max_f32_e32 v61, v62, v56
	v_min_f32_e32 v56, v62, v56
	v_max_f32_e32 v62, v63, v53
	v_min_f32_e32 v53, v63, v53
	v_max_f32_e32 v63, v54, v59
	v_min_f32_e32 v54, v54, v59
	v_max_f32_e32 v59, v52, v57
	v_min_f32_e32 v52, v52, v57
	v_max_f32_e32 v57, v49, v48
	v_min_f32_e32 v48, v49, v48
	v_max_f32_e32 v49, v51, v50
	v_min_f32_e32 v50, v51, v50
	v_min_f32_e32 v35, v39, v154
	v_max_f32_e32 v155, v42, v44
	v_min_f32_e32 v42, v42, v44
	v_max_f32_e32 v44, v45, v43
	v_min_f32_e32 v43, v45, v43
	v_max_f32_e32 v45, v40, v36
	v_min_f32_e32 v36, v40, v36
	v_max_f32_e32 v40, v46, v47
	v_min_f32_e32 v46, v46, v47
	v_max_f32_e32 v47, v37, v38
	v_min_f32_e32 v37, v37, v38
	v_max_f32_e32 v38, v41, v33
	v_min_f32_e32 v33, v41, v33
	v_max_f32_e32 v41, v32, v34
	v_min_f32_e32 v51, v55, v162
	v_max_f32_e32 v163, v58, v60
	v_min_f32_e32 v58, v58, v60
	v_max_f32_e32 v60, v61, v59
	v_min_f32_e32 v59, v61, v59
	v_max_f32_e32 v61, v56, v52
	v_min_f32_e32 v52, v56, v52
	v_max_f32_e32 v56, v62, v63
	v_min_f32_e32 v62, v62, v63
	v_max_f32_e32 v63, v53, v54
	v_min_f32_e32 v53, v53, v54
	v_max_f32_e32 v54, v57, v49
	v_min_f32_e32 v49, v57, v49
	v_max_f32_e32 v57, v48, v50
	v_min_f32_e32 v32, v32, v34
	v_max_f32_e32 v34, v155, v35
	v_min_f32_e32 v35, v155, v35
	v_max_f32_e32 v155, v42, v38
	v_min_f32_e32 v38, v42, v38
	v_max_f32_e32 v42, v44, v40
	v_min_f32_e32 v40, v44, v40
	v_max_f32_e32 v44, v45, v46
	v_min_f32_e32 v45, v45, v46
	v_max_f32_e32 v46, v47, v43
	v_min_f32_e32 v43, v47, v43
	v_max_f32_e32 v47, v37, v36
	v_min_f32_e32 v36, v37, v36
	v_max_f32_e32 v37, v41, v33
	v_min_f32_e32 v48, v48, v50
	v_max_f32_e32 v50, v163, v51
	v_min_f32_e32 v51, v163, v51
	v_max_f32_e32 v163, v58, v54
	v_min_f32_e32 v54, v58, v54
	v_max_f32_e32 v58, v60, v56
	v_min_f32_e32 v56, v60, v56
	v_max_f32_e32 v60, v61, v62
	v_min_f32_e32 v61, v61, v62
	v_max_f32_e32 v62, v63, v59
	v_min_f32_e32 v59, v63, v59
	v_max_f32_e32 v63, v53, v52
	v_min_f32_e32 v52, v53, v52
	v_max_f32_e32 v53, v57, v49
	v_min_f32_e32 v33, v41, v33
	v_max_f32_e32 v156, v35, v40
	v_min_f32_e32 v35, v35, v40
	v_max_f32_e32 v40, v44, v46
	v_min_f32_e32 v44, v44, v46
	v_max_f32_e32 v46, v45, v43
	v_min_f32_e32 v43, v45, v43
	v_max_f32_e32 v45, v47, v37
	v_min_f32_e32 v49, v57, v49
	v_max_f32_e32 v164, v51, v56
	v_min_f32_e32 v51, v51, v56
	v_max_f32_e32 v56, v60, v62
	v_min_f32_e32 v60, v60, v62
	v_max_f32_e32 v62, v61, v59
	v_min_f32_e32 v59, v61, v59
	v_max_f32_e32 v61, v63, v53
	v_min_f32_e32 v37, v47, v37
	v_max_f32_e32 v47, v36, v33
	v_max_f32_e32 v157, v155, v35
	v_min_f32_e32 v35, v155, v35
	v_max_f32_e32 v155, v45, v38
	v_min_f32_e32 v38, v45, v38
	v_min_f32_e32 v53, v63, v53
	v_max_f32_e32 v63, v52, v49
	v_max_f32_e32 v165, v163, v51
	v_min_f32_e32 v51, v163, v51
	v_max_f32_e32 v163, v61, v54
	v_min_f32_e32 v54, v61, v54
	v_min_f32_e32 v41, v34, v42
	v_max_f32_e32 v45, v47, v37
	v_min_f32_e32 v37, v47, v37
	v_max_f32_e32 v47, v157, v40
	v_min_f32_e32 v40, v157, v40
	v_max_f32_e32 v157, v35, v44
	v_min_f32_e32 v35, v35, v44
	v_max_f32_e32 v44, v46, v155
	v_min_f32_e32 v46, v46, v155
	v_max_f32_e32 v155, v43, v38
	v_min_f32_e32 v57, v50, v58
	v_max_f32_e32 v61, v63, v53
	v_min_f32_e32 v53, v63, v53
	v_max_f32_e32 v63, v165, v56
	v_min_f32_e32 v56, v165, v56
	v_max_f32_e32 v165, v51, v60
	v_min_f32_e32 v51, v51, v60
	v_max_f32_e32 v60, v62, v163
	v_min_f32_e32 v62, v62, v163
	v_max_f32_e32 v163, v59, v54
	v_min_f32_e32 v33, v36, v33
	v_min_f32_e32 v36, v156, v41
	v_min_f32_e32 v38, v43, v38
	v_min_f32_e32 v158, v40, v157
	v_max_f32_e32 v159, v44, v35
	v_min_f32_e32 v35, v44, v35
	v_max_f32_e32 v44, v46, v155
	v_min_f32_e32 v49, v52, v49
	v_min_f32_e32 v52, v164, v57
	v_min_f32_e32 v54, v59, v54
	v_min_f32_e32 v166, v56, v165
	v_max_f32_e32 v167, v60, v51
	v_min_f32_e32 v51, v60, v51
	v_max_f32_e32 v60, v62, v163
	v_min_f32_e32 v43, v47, v36
	v_min_f32_e32 v46, v46, v155
	v_min_f32_e32 v155, v45, v38
	v_min_f32_e32 v160, v158, v159
	v_min_f32_e32 v161, v35, v44
	v_min_f32_e32 v59, v63, v52
	v_min_f32_e32 v62, v62, v163
	v_min_f32_e32 v163, v61, v54
	v_min_f32_e32 v168, v166, v167
	v_min_f32_e32 v169, v51, v60
	v_max3_f32 v39, v39, v154, v48
	v_max3_f32 v34, v34, v42, v49
	v_max3_f32 v41, v156, v41, v53
	v_max3_f32 v36, v47, v36, v163
	v_max3_f32 v42, v43, v61, v54
	v_max3_f32 v40, v40, v157, v62
	v_max3_f32 v43, v158, v159, v169
	v_max3_f32 v47, v160, v51, v60
	v_max3_f32 v35, v35, v44, v168
	v_max3_f32 v44, v161, v166, v167
	v_max3_f32 v46, v46, v56, v165
	v_max3_f32 v38, v45, v38, v59
	v_max3_f32 v45, v155, v63, v52
	v_max3_f32 v37, v37, v164, v57
	v_max3_f32 v33, v33, v50, v58
	v_max3_f32 v32, v32, v55, v162
	v_max_f32_e32 v48, v39, v35
	v_min_f32_e32 v35, v39, v35
	v_max_f32_e32 v39, v34, v44
	v_min_f32_e32 v34, v34, v44
	v_max_f32_e32 v44, v41, v46
	v_min_f32_e32 v41, v41, v46
	v_max_f32_e32 v46, v36, v38
	v_min_f32_e32 v36, v36, v38
	v_max_f32_e32 v38, v42, v45
	v_min_f32_e32 v42, v42, v45
	v_max_f32_e32 v45, v40, v37
	v_min_f32_e32 v37, v40, v37
	v_max_f32_e32 v40, v43, v33
	v_min_f32_e32 v33, v43, v33
	v_max_f32_e32 v43, v47, v32
	v_min_f32_e32 v32, v47, v32
	v_max_f32_e32 v47, v48, v38
	v_min_f32_e32 v38, v48, v38
	v_max_f32_e32 v48, v39, v45
	v_min_f32_e32 v39, v39, v45
	v_max_f32_e32 v45, v44, v40
	v_min_f32_e32 v40, v44, v40
	v_max_f32_e32 v44, v46, v43
	v_min_f32_e32 v43, v46, v43
	v_max_f32_e32 v46, v35, v42
	v_min_f32_e32 v35, v35, v42
	v_max_f32_e32 v42, v34, v37
	v_min_f32_e32 v34, v34, v37
	v_max_f32_e32 v37, v41, v33
	v_min_f32_e32 v33, v41, v33
	v_max_f32_e32 v41, v36, v32
	v_min_f32_e32 v32, v36, v32
	v_max_f32_e32 v36, v47, v45
	v_min_f32_e32 v45, v47, v45
	v_max_f32_e32 v47, v48, v44
	v_min_f32_e32 v44, v48, v44
	v_max_f32_e32 v48, v38, v40
	v_min_f32_e32 v40, v38, v40
	v_max_f32_e32 v38, v39, v43
	v_min_f32_e32 v39, v39, v43
	v_max_f32_e32 v43, v46, v37
	v_min_f32_e32 v46, v46, v37
	v_max_f32_e32 v51, v35, v33
	v_min_f32_e32 v52, v35, v33
	v_max_f32_e32 v53, v34, v32
	v_min_f32_e32 v54, v34, v32
	v_max_f32_e32 v32, v36, v47
	v_min_f32_e32 v33, v36, v47
	v_max_f32_e32 v36, v48, v38
	v_min_f32_e32 v37, v48, v38
	v_lshlrev_b32_e32 v48, 2, v137
	v_max_f32_e32 v49, v42, v41
	v_and_b32_e32 v48, 0x17c, v48
	v_min_f32_e32 v50, v42, v41
	v_max_f32_e32 v38, v40, v39
	v_min_f32_e32 v39, v40, v39
	v_max_f32_e32 v40, v43, v49
	v_min_f32_e32 v41, v43, v49
	v_or3_b32 v49, v135, v48, v133
	v_lshlrev_b32_e32 v49, 6, v49
	v_max_f32_e32 v34, v45, v44
	v_min_f32_e32 v35, v45, v44
	v_mad_i32_i24 v49, v132, s75, v49
	v_max_f32_e32 v42, v46, v50
	v_min_f32_e32 v43, v46, v50
	v_max_f32_e32 v44, v51, v53
	v_min_f32_e32 v45, v51, v53
	v_max_f32_e32 v46, v52, v54
	v_min_f32_e32 v47, v52, v54
	v_bfe_u32 v240, v49, 8, 4
	v_lshlrev_b32_e32 v240, 4, v240
	v_xor_b32_e32 v240, v49, v240
	ds_write_b128 v240, v[32:35]
	v_xor_b32_e32 v241, 16, v240
	ds_write_b128 v241, v[36:39]
	v_xor_b32_e32 v241, 32, v240
	ds_write_b128 v241, v[40:43]
	v_xor_b32_e32 v241, 48, v240
	ds_write_b128 v241, v[44:47]
	v_and_b32_e32 v16, s86, v16
	v_and_b32_e32 v17, s86, v17
	v_and_b32_e32 v18, s86, v18
	v_and_b32_e32 v19, s86, v19
	v_and_b32_e32 v20, s86, v20
	v_and_b32_e32 v21, s86, v21
	v_and_b32_e32 v22, s86, v22
	v_and_b32_e32 v23, s86, v23
	v_and_b32_e32 v24, s86, v24
	v_and_b32_e32 v25, s86, v25
	v_and_b32_e32 v26, s86, v26
	v_and_b32_e32 v27, s86, v27
	v_and_b32_e32 v28, s86, v28
	v_and_b32_e32 v29, s86, v29
	v_and_b32_e32 v30, s86, v30
	v_and_b32_e32 v31, s86, v31
	v_and_or_b32 v0, v0, s86, v138
	v_and_or_b32 v1, v1, s86, v139
	v_and_or_b32 v2, v2, s86, v140
	v_and_or_b32 v3, v3, s86, v141
	v_and_or_b32 v4, v4, s86, v142
	v_and_or_b32 v5, v5, s86, v143
	v_and_or_b32 v6, v6, s86, v144
	v_and_or_b32 v7, v7, s86, v145
	v_and_or_b32 v8, v8, s86, v146
	v_and_or_b32 v9, v9, s86, v147
	v_and_or_b32 v10, v10, s86, v148
	v_and_or_b32 v11, v11, s86, v149
	v_and_or_b32 v12, v12, s86, v150
	v_and_or_b32 v13, v13, s86, v151
	v_and_or_b32 v14, v14, s86, v152
	v_and_or_b32 v15, v15, s86, v153
	v_or3_b32 v16, v136, v16, v138
	v_or3_b32 v0, v0, v136, 32
	v_or3_b32 v17, v136, v17, v139
	v_or3_b32 v1, v1, v136, 32
	v_or3_b32 v18, v136, v18, v140
	v_or3_b32 v2, v2, v136, 32
	v_or3_b32 v19, v136, v19, v141
	v_or3_b32 v3, v3, v136, 32
	v_or3_b32 v20, v136, v20, v142
	v_or3_b32 v4, v4, v136, 32
	v_or3_b32 v21, v136, v21, v143
	v_or3_b32 v5, v5, v136, 32
	v_or3_b32 v22, v136, v22, v144
	v_or3_b32 v6, v6, v136, 32
	v_or3_b32 v23, v136, v23, v145
	v_or3_b32 v7, v7, v136, 32
	v_or3_b32 v24, v136, v24, v146
	v_or3_b32 v8, v8, v136, 32
	v_or3_b32 v25, v136, v25, v147
	v_or3_b32 v9, v9, v136, 32
	v_or3_b32 v26, v136, v26, v148
	v_or3_b32 v10, v10, v136, 32
	v_or3_b32 v27, v136, v27, v149
	v_or3_b32 v11, v11, v136, 32
	v_or3_b32 v28, v136, v28, v150
	v_or3_b32 v12, v12, v136, 32
	v_or3_b32 v29, v136, v29, v151
	v_or3_b32 v13, v13, v136, 32
	v_or3_b32 v30, v136, v30, v152
	v_or3_b32 v14, v14, v136, 32
	v_or3_b32 v31, v136, v31, v153
	v_or3_b32 v15, v15, v136, 32
	v_max_f32_e32 v32, v16, v29
	v_min_f32_e32 v16, v16, v29
	v_max_f32_e32 v29, v17, v28
	v_min_f32_e32 v17, v17, v28
	v_max_f32_e32 v28, v18, v31
	v_min_f32_e32 v18, v18, v31
	v_max_f32_e32 v31, v19, v30
	v_min_f32_e32 v19, v19, v30
	v_max_f32_e32 v30, v20, v24
	v_min_f32_e32 v20, v20, v24
	v_max_f32_e32 v24, v21, v22
	v_min_f32_e32 v21, v21, v22
	v_max_f32_e32 v22, v23, v27
	v_min_f32_e32 v23, v23, v27
	v_max_f32_e32 v27, v25, v26
	v_min_f32_e32 v25, v25, v26
	v_max_f32_e32 v40, v0, v13
	v_min_f32_e32 v0, v0, v13
	v_max_f32_e32 v13, v1, v12
	v_min_f32_e32 v1, v1, v12
	v_max_f32_e32 v12, v2, v15
	v_min_f32_e32 v2, v2, v15
	v_max_f32_e32 v15, v3, v14
	v_min_f32_e32 v3, v3, v14
	v_max_f32_e32 v14, v4, v8
	v_min_f32_e32 v4, v4, v8
	v_max_f32_e32 v8, v5, v6
	v_min_f32_e32 v5, v5, v6
	v_max_f32_e32 v6, v7, v11
	v_min_f32_e32 v7, v7, v11
	v_max_f32_e32 v11, v9, v10
	v_min_f32_e32 v9, v9, v10
	v_max_f32_e32 v26, v32, v24
	v_min_f32_e32 v24, v32, v24
	v_max_f32_e32 v32, v29, v22
	v_min_f32_e32 v22, v29, v22
	v_max_f32_e32 v29, v28, v27
	v_min_f32_e32 v27, v28, v27
	v_max_f32_e32 v28, v31, v30
	v_min_f32_e32 v30, v31, v30
	v_max_f32_e32 v31, v21, v16
	v_min_f32_e32 v16, v21, v16
	v_max_f32_e32 v21, v20, v19
	v_min_f32_e32 v19, v20, v19
	v_max_f32_e32 v20, v25, v18
	v_min_f32_e32 v18, v25, v18
	v_max_f32_e32 v25, v23, v17
	v_min_f32_e32 v17, v23, v17
	v_max_f32_e32 v10, v40, v8
	v_min_f32_e32 v8, v40, v8
	v_max_f32_e32 v40, v13, v6
	v_min_f32_e32 v6, v13, v6
	v_max_f32_e32 v13, v12, v11
	v_min_f32_e32 v11, v12, v11
	v_max_f32_e32 v12, v15, v14
	v_min_f32_e32 v14, v15, v14
	v_max_f32_e32 v15, v5, v0
	v_min_f32_e32 v0, v5, v0
	v_max_f32_e32 v5, v4, v3
	v_min_f32_e32 v3, v4, v3
	v_max_f32_e32 v4, v9, v2
	v_min_f32_e32 v2, v9, v2
	v_max_f32_e32 v9, v7, v1
	v_min_f32_e32 v1, v7, v1
	v_max_f32_e32 v23, v26, v32
	v_min_f32_e32 v26, v26, v32
	v_max_f32_e32 v32, v29, v28
	v_min_f32_e32 v28, v29, v28
	v_max_f32_e32 v29, v30, v24
	v_min_f32_e32 v24, v30, v24
	v_max_f32_e32 v30, v31, v21
	v_min_f32_e32 v21, v31, v21
	v_max_f32_e32 v31, v22, v27
	v_min_f32_e32 v22, v22, v27
	v_max_f32_e32 v27, v20, v25
	v_min_f32_e32 v20, v20, v25
	v_max_f32_e32 v25, v17, v16
	v_min_f32_e32 v16, v17, v16
	v_max_f32_e32 v17, v19, v18
	v_min_f32_e32 v18, v19, v18
	v_max_f32_e32 v7, v10, v40
	v_min_f32_e32 v10, v10, v40
	v_max_f32_e32 v40, v13, v12
	v_min_f32_e32 v12, v13, v12
	v_max_f32_e32 v13, v14, v8
	v_min_f32_e32 v8, v14, v8
	v_max_f32_e32 v14, v15, v5
	v_min_f32_e32 v5, v15, v5
	v_max_f32_e32 v15, v6, v11
	v_min_f32_e32 v6, v6, v11
	v_max_f32_e32 v11, v4, v9
	v_min_f32_e32 v4, v4, v9
	v_max_f32_e32 v9, v1, v0
	v_min_f32_e32 v0, v1, v0
	v_max_f32_e32 v1, v3, v2
	v_min_f32_e32 v2, v3, v2
	v_min_f32_e32 v19, v23, v32
	v_max_f32_e32 v33, v26, v28
	v_min_f32_e32 v26, v26, v28
	v_max_f32_e32 v28, v29, v27
	v_min_f32_e32 v27, v29, v27
	v_max_f32_e32 v29, v24, v20
	v_min_f32_e32 v20, v24, v20
	v_max_f32_e32 v24, v30, v31
	v_min_f32_e32 v30, v30, v31
	v_max_f32_e32 v31, v21, v22
	v_min_f32_e32 v21, v21, v22
	v_max_f32_e32 v22, v25, v17
	v_min_f32_e32 v17, v25, v17
	v_max_f32_e32 v25, v16, v18
	v_min_f32_e32 v3, v7, v40
	v_max_f32_e32 v41, v10, v12
	v_min_f32_e32 v10, v10, v12
	v_max_f32_e32 v12, v13, v11
	v_min_f32_e32 v11, v13, v11
	v_max_f32_e32 v13, v8, v4
	v_min_f32_e32 v4, v8, v4
	v_max_f32_e32 v8, v14, v15
	v_min_f32_e32 v14, v14, v15
	v_max_f32_e32 v15, v5, v6
	v_min_f32_e32 v5, v5, v6
	v_max_f32_e32 v6, v9, v1
	v_min_f32_e32 v1, v9, v1
	v_max_f32_e32 v9, v0, v2
	v_min_f32_e32 v16, v16, v18
	v_max_f32_e32 v18, v33, v19
	v_min_f32_e32 v19, v33, v19
	v_max_f32_e32 v33, v26, v22
	v_min_f32_e32 v22, v26, v22
	v_max_f32_e32 v26, v28, v24
	v_min_f32_e32 v24, v28, v24
	v_max_f32_e32 v28, v29, v30
	v_min_f32_e32 v29, v29, v30
	v_max_f32_e32 v30, v31, v27
	v_min_f32_e32 v27, v31, v27
	v_max_f32_e32 v31, v21, v20
	v_min_f32_e32 v20, v21, v20
	v_max_f32_e32 v21, v25, v17
	v_min_f32_e32 v0, v0, v2
	v_max_f32_e32 v2, v41, v3
	v_min_f32_e32 v3, v41, v3
	v_max_f32_e32 v41, v10, v6
	v_min_f32_e32 v6, v10, v6
	v_max_f32_e32 v10, v12, v8
	v_min_f32_e32 v8, v12, v8
	v_max_f32_e32 v12, v13, v14
	v_min_f32_e32 v13, v13, v14
	v_max_f32_e32 v14, v15, v11
	v_min_f32_e32 v11, v15, v11
	v_max_f32_e32 v15, v5, v4
	v_min_f32_e32 v4, v5, v4
	v_max_f32_e32 v5, v9, v1
	v_min_f32_e32 v17, v25, v17
	v_max_f32_e32 v34, v19, v24
	v_min_f32_e32 v19, v19, v24
	v_max_f32_e32 v24, v28, v30
	v_min_f32_e32 v28, v28, v30
	v_max_f32_e32 v30, v29, v27
	v_min_f32_e32 v27, v29, v27
	v_max_f32_e32 v29, v31, v21
	v_min_f32_e32 v1, v9, v1
	v_max_f32_e32 v42, v3, v8
	v_min_f32_e32 v3, v3, v8
	v_max_f32_e32 v8, v12, v14
	v_min_f32_e32 v12, v12, v14
	v_max_f32_e32 v14, v13, v11
	v_min_f32_e32 v11, v13, v11
	v_max_f32_e32 v13, v15, v5
	v_min_f32_e32 v21, v31, v21
	v_max_f32_e32 v31, v20, v17
	v_max_f32_e32 v35, v33, v19
	v_min_f32_e32 v19, v33, v19
	v_max_f32_e32 v33, v29, v22
	v_min_f32_e32 v22, v29, v22
	v_min_f32_e32 v5, v15, v5
	v_max_f32_e32 v15, v4, v1
	v_max_f32_e32 v43, v41, v3
	v_min_f32_e32 v3, v41, v3
	v_max_f32_e32 v41, v13, v6
	v_min_f32_e32 v6, v13, v6
	v_min_f32_e32 v25, v18, v26
	v_max_f32_e32 v29, v31, v21
	v_min_f32_e32 v21, v31, v21
	v_max_f32_e32 v31, v35, v24
	v_min_f32_e32 v24, v35, v24
	v_max_f32_e32 v35, v19, v28
	v_min_f32_e32 v19, v19, v28
	v_max_f32_e32 v28, v30, v33
	v_min_f32_e32 v30, v30, v33
	v_max_f32_e32 v33, v27, v22
	v_min_f32_e32 v9, v2, v10
	v_max_f32_e32 v13, v15, v5
	v_min_f32_e32 v5, v15, v5
	v_max_f32_e32 v15, v43, v8
	v_min_f32_e32 v8, v43, v8
	v_max_f32_e32 v43, v3, v12
	v_min_f32_e32 v3, v3, v12
	v_max_f32_e32 v12, v14, v41
	v_min_f32_e32 v14, v14, v41
	v_max_f32_e32 v41, v11, v6
	v_min_f32_e32 v17, v20, v17
	v_min_f32_e32 v20, v34, v25
	v_min_f32_e32 v22, v27, v22
	v_min_f32_e32 v36, v24, v35
	v_max_f32_e32 v37, v28, v19
	v_min_f32_e32 v19, v28, v19
	v_max_f32_e32 v28, v30, v33
	v_min_f32_e32 v1, v4, v1
	v_min_f32_e32 v4, v42, v9
	v_min_f32_e32 v6, v11, v6
	v_min_f32_e32 v44, v8, v43
	v_max_f32_e32 v45, v12, v3
	v_min_f32_e32 v3, v12, v3
	v_max_f32_e32 v12, v14, v41
	v_min_f32_e32 v27, v31, v20
	v_min_f32_e32 v30, v30, v33
	v_min_f32_e32 v33, v29, v22
	v_min_f32_e32 v38, v36, v37
	v_min_f32_e32 v39, v19, v28
	v_min_f32_e32 v11, v15, v4
	v_min_f32_e32 v14, v14, v41
	v_min_f32_e32 v41, v13, v6
	v_min_f32_e32 v46, v44, v45
	v_min_f32_e32 v47, v3, v12
	v_max3_f32 v0, v23, v32, v0
	v_max3_f32 v1, v18, v26, v1
	v_max3_f32 v5, v34, v25, v5
	v_max3_f32 v18, v31, v20, v41
	v_max3_f32 v6, v27, v13, v6
	v_max3_f32 v13, v24, v35, v14
	v_max3_f32 v14, v36, v37, v47
	v_max3_f32 v3, v38, v3, v12
	v_max3_f32 v12, v19, v28, v46
	v_max3_f32 v19, v39, v44, v45
	v_max3_f32 v8, v30, v8, v43
	v_max3_f32 v11, v29, v22, v11
	v_max3_f32 v4, v33, v15, v4
	v_max3_f32 v9, v21, v42, v9
	v_max3_f32 v2, v17, v2, v10
	v_max3_f32 v7, v16, v7, v40
	v_max_f32_e32 v10, v0, v12
	v_min_f32_e32 v0, v0, v12
	v_max_f32_e32 v12, v1, v19
	v_max_f32_e32 v15, v5, v8
	v_min_f32_e32 v5, v5, v8
	v_max_f32_e32 v8, v18, v11
	v_max_f32_e32 v16, v6, v4
	v_min_f32_e32 v4, v6, v4
	v_max_f32_e32 v6, v13, v9
	v_min_f32_e32 v9, v13, v9
	v_max_f32_e32 v13, v14, v2
	v_min_f32_e32 v2, v14, v2
	v_max_f32_e32 v14, v3, v7
	v_min_f32_e32 v1, v1, v19
	v_min_f32_e32 v11, v18, v11
	v_min_f32_e32 v3, v3, v7
	v_max_f32_e32 v7, v10, v16
	v_min_f32_e32 v10, v10, v16
	v_max_f32_e32 v16, v12, v6
	v_min_f32_e32 v6, v12, v6
	v_max_f32_e32 v12, v15, v13
	v_min_f32_e32 v13, v15, v13
	v_max_f32_e32 v15, v8, v14
	v_min_f32_e32 v8, v8, v14
	v_max_f32_e32 v14, v0, v4
	v_min_f32_e32 v0, v0, v4
	v_max_f32_e32 v4, v1, v9
	v_min_f32_e32 v1, v1, v9
	v_max_f32_e32 v9, v5, v2
	v_min_f32_e32 v2, v5, v2
	v_max_f32_e32 v5, v11, v3
	v_min_f32_e32 v3, v11, v3
	v_max_f32_e32 v11, v7, v12
	v_min_f32_e32 v7, v7, v12
	v_max_f32_e32 v12, v16, v15
	v_min_f32_e32 v15, v16, v15
	v_max_f32_e32 v16, v10, v13
	v_min_f32_e32 v10, v10, v13
	v_max_f32_e32 v13, v6, v8
	v_max_f32_e32 v17, v14, v9
	v_min_f32_e32 v14, v14, v9
	v_max_f32_e32 v9, v4, v5
	v_min_f32_e32 v18, v4, v5
	v_max_f32_e32 v4, v16, v13
	v_min_f32_e32 v5, v16, v13
	v_or3_b32 v16, v133, v48, v135
	v_lshlrev_b32_e32 v16, 6, v16
	v_min_f32_e32 v8, v6, v8
	v_max_f32_e32 v19, v0, v2
	v_min_f32_e32 v20, v0, v2
	v_max_f32_e32 v21, v1, v3
	v_min_f32_e32 v22, v1, v3
	v_max_f32_e32 v0, v11, v12
	v_min_f32_e32 v1, v11, v12
	v_max_f32_e32 v2, v7, v15
	v_min_f32_e32 v3, v7, v15
	v_mad_i32_i24 v16, v132, s75, v16
	v_max_f32_e32 v6, v10, v8
	v_min_f32_e32 v7, v10, v8
	v_max_f32_e32 v8, v17, v9
	v_min_f32_e32 v9, v17, v9
	v_max_f32_e32 v10, v14, v18
	v_min_f32_e32 v11, v14, v18
	v_max_f32_e32 v12, v19, v21
	v_min_f32_e32 v13, v19, v21
	v_max_f32_e32 v14, v20, v22
	v_min_f32_e32 v15, v20, v22
	v_bfe_u32 v240, v16, 8, 4
	v_lshlrev_b32_e32 v240, 4, v240
	v_xor_b32_e32 v240, v16, v240
	ds_write_b128 v240, v[0:3] offset:8192
	v_xor_b32_e32 v241, 16, v240
	ds_write_b128 v241, v[4:7] offset:8192
	v_xor_b32_e32 v241, 32, v240
	ds_write_b128 v241, v[8:11] offset:8192
	v_xor_b32_e32 v241, 48, v240
	ds_write_b128 v241, v[12:15] offset:8192
	s_waitcnt lgkmcnt(0)
	s_barrier
	s_and_saveexec_b64 s[62:63], vcc
	s_cbranch_execz .LBB0_867
	v_lshl_add_u32 v60, v128, 8, v131
	v_bfe_u32 v240, v60, 8, 4
	v_lshlrev_b32_e32 v240, 4, v240
	v_xor_b32_e32 v240, v60, v240
	ds_read_b128 v[0:3], v240
	v_xor_b32_e32 v241, 16, v240
	ds_read_b128 v[4:7], v241
	v_xor_b32_e32 v241, 32, v240
	ds_read_b128 v[8:11], v241
	v_xor_b32_e32 v241, 48, v240
	ds_read_b128 v[12:15], v241
	v_xor_b32_e32 v241, 64, v240
	ds_read_b128 v[16:19], v241
	v_xor_b32_e32 v241, 0x50, v240
	ds_read_b128 v[20:23], v241
	v_xor_b32_e32 v241, 0x80, v240
	ds_read_b128 v[24:27], v241
	v_xor_b32_e32 v241, 0x90, v240
	ds_read_b128 v[28:31], v241
	v_xor_b32_e32 v241, 0xc0, v240
	ds_read_b128 v[32:35], v241
	v_xor_b32_e32 v241, 0xd0, v240
	ds_read_b128 v[36:39], v241
	v_xor_b32_e32 v241, 0x60, v240
	ds_read_b128 v[40:43], v241
	v_xor_b32_e32 v241, 0x70, v240
	ds_read_b128 v[44:47], v241
	v_xor_b32_e32 v241, 0xa0, v240
	ds_read_b128 v[48:51], v241
	v_xor_b32_e32 v241, 0xb0, v240
	ds_read_b128 v[52:55], v241
	v_xor_b32_e32 v241, 0xe0, v240
	ds_read_b128 v[56:59], v241
	v_xor_b32_e32 v241, 0xf0, v240
	ds_read_b128 v[60:63], v241
	s_waitcnt lgkmcnt(4)
	v_max_f32_e32 v0, v0, v47
	v_max_f32_e32 v1, v1, v46
	v_max_f32_e32 v2, v2, v45
	v_max_f32_e32 v3, v3, v44
	v_max_f32_e32 v4, v4, v43
	v_max_f32_e32 v5, v5, v42
	v_max_f32_e32 v6, v6, v41
	v_max_f32_e32 v7, v7, v40
	v_max_f32_e32 v8, v8, v23
	v_max_f32_e32 v9, v9, v22
	v_max_f32_e32 v10, v10, v21
	v_max_f32_e32 v11, v11, v20
	v_max_f32_e32 v12, v12, v19
	v_max_f32_e32 v13, v13, v18
	v_max_f32_e32 v14, v14, v17
	v_max_f32_e32 v15, v15, v16
	s_waitcnt lgkmcnt(0)
	v_max_f32_e32 v24, v24, v63
	v_max_f32_e32 v25, v25, v62
	v_max_f32_e32 v26, v26, v61
	v_max_f32_e32 v27, v27, v60
	v_max_f32_e32 v28, v28, v59
	v_max_f32_e32 v29, v29, v58
	v_max_f32_e32 v30, v30, v57
	v_max_f32_e32 v31, v31, v56
	v_max_f32_e32 v39, v48, v39
	v_max_f32_e32 v38, v49, v38
	v_max_f32_e32 v37, v50, v37
	v_max_f32_e32 v36, v51, v36
	v_max_f32_e32 v35, v52, v35
	v_max_f32_e32 v34, v53, v34
	v_max_f32_e32 v33, v54, v33
	v_max_f32_e32 v32, v55, v32
	v_max_f32_e32 v16, v0, v8
	v_min_f32_e32 v0, v0, v8
	v_max_f32_e32 v8, v1, v9
	v_min_f32_e32 v1, v1, v9
	v_max_f32_e32 v9, v2, v10
	v_min_f32_e32 v2, v2, v10
	v_max_f32_e32 v10, v3, v11
	v_min_f32_e32 v3, v3, v11
	v_max_f32_e32 v11, v4, v12
	v_min_f32_e32 v4, v4, v12
	v_max_f32_e32 v12, v5, v13
	v_min_f32_e32 v5, v5, v13
	v_max_f32_e32 v13, v6, v14
	v_min_f32_e32 v6, v6, v14
	v_max_f32_e32 v14, v7, v15
	v_min_f32_e32 v7, v7, v15
	v_max_f32_e32 v40, v24, v39
	v_min_f32_e32 v24, v24, v39
	v_max_f32_e32 v39, v25, v38
	v_min_f32_e32 v25, v25, v38
	v_max_f32_e32 v38, v26, v37
	v_min_f32_e32 v26, v26, v37
	v_max_f32_e32 v37, v27, v36
	v_min_f32_e32 v27, v27, v36
	v_max_f32_e32 v36, v28, v35
	v_min_f32_e32 v28, v28, v35
	v_max_f32_e32 v35, v29, v34
	v_min_f32_e32 v29, v29, v34
	v_max_f32_e32 v34, v30, v33
	v_min_f32_e32 v30, v30, v33
	v_max_f32_e32 v33, v31, v32
	v_min_f32_e32 v31, v31, v32
	v_max_f32_e32 v15, v16, v11
	v_min_f32_e32 v11, v16, v11
	v_max_f32_e32 v16, v8, v12
	v_min_f32_e32 v8, v8, v12
	v_max_f32_e32 v12, v9, v13
	v_min_f32_e32 v9, v9, v13
	v_max_f32_e32 v13, v10, v14
	v_min_f32_e32 v10, v10, v14
	v_max_f32_e32 v14, v0, v4
	v_min_f32_e32 v0, v0, v4
	v_max_f32_e32 v4, v1, v5
	v_min_f32_e32 v1, v1, v5
	v_max_f32_e32 v5, v2, v6
	v_min_f32_e32 v2, v2, v6
	v_max_f32_e32 v6, v3, v7
	v_min_f32_e32 v3, v3, v7
	v_max_f32_e32 v32, v40, v36
	v_min_f32_e32 v36, v40, v36
	v_max_f32_e32 v40, v39, v35
	v_min_f32_e32 v35, v39, v35
	v_max_f32_e32 v39, v38, v34
	v_min_f32_e32 v34, v38, v34
	v_max_f32_e32 v38, v37, v33
	v_min_f32_e32 v33, v37, v33
	v_max_f32_e32 v37, v24, v28
	v_min_f32_e32 v24, v24, v28
	v_max_f32_e32 v28, v25, v29
	v_min_f32_e32 v25, v25, v29
	v_max_f32_e32 v29, v26, v30
	v_min_f32_e32 v26, v26, v30
	v_max_f32_e32 v30, v27, v31
	v_min_f32_e32 v27, v27, v31
	v_max_f32_e32 v7, v15, v12
	v_min_f32_e32 v12, v15, v12
	v_max_f32_e32 v15, v16, v13
	v_min_f32_e32 v13, v16, v13
	v_max_f32_e32 v16, v11, v9
	v_min_f32_e32 v9, v11, v9
	v_max_f32_e32 v11, v8, v10
	v_min_f32_e32 v8, v8, v10
	v_max_f32_e32 v10, v14, v5
	v_min_f32_e32 v5, v14, v5
	v_max_f32_e32 v14, v4, v6
	v_min_f32_e32 v4, v4, v6
	v_max_f32_e32 v6, v0, v2
	v_min_f32_e32 v0, v0, v2
	v_max_f32_e32 v2, v1, v3
	v_min_f32_e32 v1, v1, v3
	v_max_f32_e32 v31, v32, v39
	v_min_f32_e32 v32, v32, v39
	v_max_f32_e32 v39, v40, v38
	v_min_f32_e32 v38, v40, v38
	v_max_f32_e32 v40, v36, v34
	v_min_f32_e32 v34, v36, v34
	v_max_f32_e32 v36, v35, v33
	v_min_f32_e32 v33, v35, v33
	v_max_f32_e32 v35, v37, v29
	v_min_f32_e32 v29, v37, v29
	v_max_f32_e32 v37, v28, v30
	v_min_f32_e32 v28, v28, v30
	v_max_f32_e32 v30, v24, v26
	v_min_f32_e32 v24, v24, v26
	v_max_f32_e32 v26, v25, v27
	v_min_f32_e32 v25, v25, v27
	v_min_f32_e32 v3, v7, v15
	v_min_f32_e32 v17, v12, v13
	v_min_f32_e32 v18, v16, v11
	v_min_f32_e32 v19, v9, v8
	v_min_f32_e32 v20, v10, v14
	v_min_f32_e32 v21, v5, v4
	v_min_f32_e32 v22, v6, v2
	v_min_f32_e32 v23, v0, v1
	v_min_f32_e32 v27, v31, v39
	v_min_f32_e32 v41, v32, v38
	v_min_f32_e32 v42, v40, v36
	v_min_f32_e32 v43, v34, v33
	v_min_f32_e32 v44, v35, v37
	v_min_f32_e32 v45, v29, v28
	v_min_f32_e32 v46, v30, v26
	v_min_f32_e32 v47, v24, v25
	v_max3_f32 v7, v7, v15, v47
	v_max3_f32 v3, v3, v24, v25
	v_max3_f32 v12, v12, v13, v46
	v_max3_f32 v13, v17, v30, v26
	v_max3_f32 v11, v16, v11, v45
	v_max3_f32 v15, v18, v29, v28
	v_max3_f32 v8, v9, v8, v44
	v_max3_f32 v9, v19, v35, v37
	v_max3_f32 v10, v10, v14, v43
	v_max3_f32 v14, v20, v34, v33
	v_max3_f32 v4, v5, v4, v42
	v_max3_f32 v5, v21, v40, v36
	v_max3_f32 v2, v6, v2, v41
	v_max3_f32 v6, v22, v32, v38
	v_max3_f32 v0, v0, v1, v27
	v_max3_f32 v1, v23, v31, v39
	v_max_f32_e32 v16, v7, v10
	v_min_f32_e32 v7, v7, v10
	v_max_f32_e32 v10, v3, v14
	v_min_f32_e32 v3, v3, v14
	v_max_f32_e32 v14, v12, v4
	v_min_f32_e32 v4, v12, v4
	v_max_f32_e32 v12, v13, v5
	v_min_f32_e32 v5, v13, v5
	v_max_f32_e32 v13, v11, v2
	v_min_f32_e32 v2, v11, v2
	v_max_f32_e32 v11, v15, v6
	v_min_f32_e32 v6, v15, v6
	v_max_f32_e32 v15, v8, v0
	v_min_f32_e32 v0, v8, v0
	v_max_f32_e32 v8, v9, v1
	v_min_f32_e32 v1, v9, v1
	v_max_f32_e32 v9, v16, v13
	v_min_f32_e32 v13, v16, v13
	v_max_f32_e32 v16, v10, v11
	v_min_f32_e32 v10, v10, v11
	v_max_f32_e32 v11, v14, v15
	v_min_f32_e32 v14, v14, v15
	v_max_f32_e32 v15, v12, v8
	v_min_f32_e32 v8, v12, v8
	v_max_f32_e32 v12, v7, v2
	v_min_f32_e32 v2, v7, v2
	v_max_f32_e32 v7, v3, v6
	v_min_f32_e32 v3, v3, v6
	v_max_f32_e32 v6, v4, v0
	v_min_f32_e32 v0, v4, v0
	v_max_f32_e32 v4, v5, v1
	v_min_f32_e32 v1, v5, v1
	v_max_f32_e32 v5, v9, v11
	v_min_f32_e32 v9, v9, v11
	v_max_f32_e32 v11, v16, v15
	v_min_f32_e32 v15, v16, v15
	v_max_f32_e32 v16, v13, v14
	v_min_f32_e32 v13, v13, v14
	v_max_f32_e32 v14, v10, v8
	v_min_f32_e32 v8, v10, v8
	v_max_f32_e32 v10, v12, v6
	v_max_f32_e32 v17, v7, v4
	v_min_f32_e32 v18, v7, v4
	v_max_f32_e32 v19, v2, v0
	v_min_f32_e32 v20, v2, v0
	v_max_f32_e32 v21, v3, v1
	v_min_f32_e32 v22, v3, v1
	v_max_f32_e32 v0, v5, v11
	v_min_f32_e32 v1, v5, v11
	v_max_f32_e32 v4, v16, v14
	v_min_f32_e32 v5, v16, v14
	v_or_b32_e32 v16, s60, v128
	v_min_f32_e32 v12, v12, v6
	v_max_f32_e32 v2, v9, v15
	v_min_f32_e32 v3, v9, v15
	v_max_f32_e32 v6, v13, v8
	v_min_f32_e32 v7, v13, v8
	v_max_f32_e32 v8, v10, v17
	v_min_f32_e32 v9, v10, v17
	v_ashrrev_i32_e32 v17, 31, v16
	v_max_f32_e32 v10, v12, v18
	v_min_f32_e32 v11, v12, v18
	v_lshlrev_b64 v[16:17], 10, v[16:17]
	v_lshlrev_b32_e32 v18, 4, v130
	v_max_f32_e32 v12, v19, v21
	v_min_f32_e32 v13, v19, v21
	v_lshl_add_u64 v[16:17], s[12:13], 0, v[16:17]
	v_ashrrev_i32_e32 v19, 31, v18
	v_lshl_add_u64 v[16:17], v[18:19], 2, v[16:17]
	v_max_f32_e32 v14, v20, v22
	v_min_f32_e32 v15, v20, v22
	v_and_b32_e32 v238, 3, v128
	v_lshl_add_u32 v239, v128, 8, v131
	v_lshl_add_u32 v239, v238, 6, v239
	ds_write_b128 v239, v[0:3]
	ds_write_b128 v239, v[4:7] offset:16
	ds_write_b128 v239, v[8:11] offset:32
	ds_write_b128 v239, v[12:15] offset:48
	v_bfe_u32 v242, v128, 2, 4
	v_and_or_b32 v242, v128, 64, v242
	v_and_b32_e32 v243, 3, v242
	v_lshlrev_b32_e32 v243, 6, v243
	v_lshl_add_u32 v243, v238, 4, v243
	v_lshl_add_u32 v243, v242, 8, v243
	v_add_u32_e32 v243, v131, v243
	ds_read_b128 v[20:23], v243
	ds_read_b128 v[24:27], v243 offset:4096
	ds_read_b128 v[28:31], v243 offset:8192
	ds_read_b128 v[32:35], v243 offset:12288
	v_or_b32_e32 v244, s60, v242
	v_ashrrev_i32_e32 v245, 31, v244
	v_lshlrev_b64 v[244:245], 10, v[244:245]
	v_lshl_add_u64 v[244:245], s[12:13], 0, v[244:245]
	v_lshl_add_u64 v[244:245], v[18:19], 2, v[244:245]
	v_lshlrev_b32_e32 v246, 4, v238
	v_mov_b32_e32 v247, 0
	v_lshl_add_u64 v[244:245], v[244:245], 0, v[246:247]
	v_mov_b32_e32 v246, 0x4000
	s_waitcnt lgkmcnt(3)
	global_store_dwordx4 v[244:245], v[20:23], off
	v_lshl_add_u64 v[244:245], v[244:245], 0, v[246:247]
	s_waitcnt lgkmcnt(2)
	global_store_dwordx4 v[244:245], v[24:27], off
	v_lshl_add_u64 v[244:245], v[244:245], 0, v[246:247]
	s_waitcnt lgkmcnt(1)
	global_store_dwordx4 v[244:245], v[28:31], off
	v_lshl_add_u64 v[244:245], v[244:245], 0, v[246:247]
	s_waitcnt lgkmcnt(0)
	global_store_dwordx4 v[244:245], v[32:35], off
.LBB0_867:
	s_or_b64 exec, exec, s[62:63]
	v_mov_b32_e32 v0, v176
	s_barrier
	v_cvt_pk_bf16_f32 v124, v124, v125
	v_cvt_pk_bf16_f32 v125, v126, v127
	v_cvt_pk_bf16_f32 v116, v116, v117
	v_cvt_pk_bf16_f32 v117, v118, v119
	v_cvt_pk_bf16_f32 v120, v120, v121
	v_cvt_pk_bf16_f32 v121, v122, v123
	v_cvt_pk_bf16_f32 v112, v112, v113
	v_cvt_pk_bf16_f32 v113, v114, v115
	v_cvt_pk_bf16_f32 v108, v108, v109
	v_cvt_pk_bf16_f32 v109, v110, v111
	v_cvt_pk_bf16_f32 v96, v96, v97
	v_cvt_pk_bf16_f32 v97, v98, v99
	v_cvt_pk_bf16_f32 v104, v104, v105
	v_cvt_pk_bf16_f32 v105, v106, v107
	v_cvt_pk_bf16_f32 v88, v88, v89
	v_cvt_pk_bf16_f32 v89, v90, v91
	v_cvt_pk_bf16_f32 v100, v100, v101
	v_cvt_pk_bf16_f32 v101, v102, v103
	v_cvt_pk_bf16_f32 v92, v92, v93
	v_cvt_pk_bf16_f32 v93, v94, v95
	v_cvt_pk_bf16_f32 v84, v84, v85
	v_cvt_pk_bf16_f32 v85, v86, v87
	v_cvt_pk_bf16_f32 v80, v80, v81
	v_cvt_pk_bf16_f32 v81, v82, v83
	v_cvt_pk_bf16_f32 v76, v76, v77
	v_cvt_pk_bf16_f32 v77, v78, v79
	v_cvt_pk_bf16_f32 v72, v72, v73
	v_cvt_pk_bf16_f32 v73, v74, v75
	v_cvt_pk_bf16_f32 v68, v68, v69
	v_cvt_pk_bf16_f32 v69, v70, v71
	v_cvt_pk_bf16_f32 v64, v64, v65
	v_cvt_pk_bf16_f32 v65, v66, v67
	v_and_b32_e32 v1, 15, v0
	v_lshrrev_b32_e32 v2, 1, v0
	v_and_or_b32 v2, v2, s81, v1
	v_ashrrev_i32_e32 v1, 2, v0
	v_lshrrev_b32_e32 v0, 2, v0
	v_and_b32_e32 v0, 12, v0
	v_and_or_b32 v3, v1, s82, v0
	v_mul_u32_u24_e32 v2, 0x110, v2
	v_lshl_add_u32 v6, v3, 1, v2
	v_add_u32_e32 v7, 0x8000, v6
	ds_write2_b64 v7, v[124:125], v[116:117] offset1:4
	v_add_u32_e32 v8, 0x9000, v6
	ds_write2_b64 v8, v[120:121], v[112:113] offset0:32 offset1:36
	ds_write2_b64 v7, v[108:109], v[96:97] offset0:8 offset1:12
	ds_write2_b64 v8, v[104:105], v[88:89] offset0:40 offset1:44
	v_add_u32_e32 v2, 0x1a000, v6
	ds_write_b64 v2, v[100:101]
	ds_write_b64 v2, v[92:93] offset:4352
	v_add_u32_e32 v2, 0x1a020, v6
	ds_write_b64 v2, v[84:85]
	ds_write_b64 v2, v[80:81] offset:4352
	v_add_u32_e32 v2, 0x1a040, v6
	ds_write_b64 v2, v[76:77]
	ds_write_b64 v2, v[72:73] offset:4352
	v_add_u32_e32 v2, 0x1a060, v6
	ds_write_b64 v2, v[68:69]
	v_mov_b32_e32 v71, v176
	ds_write_b64 v2, v[64:65] offset:4352
	s_nop 0
	v_ashrrev_i32_e32 v67, 8, v71
	v_add_u32_e32 v64, s59, v67
	v_bfe_u32 v69, v71, 7, 1
	v_ashrrev_i32_e32 v65, 31, v64
	v_and_b32_e32 v2, 31, v71
	v_lshlrev_b64 v[0:1], 7, v[64:65]
	v_lshlrev_b32_e32 v70, 6, v69
	v_or3_b32 v0, v0, v70, v2
	v_bfe_u32 v68, v71, 5, 1
	v_lshlrev_b64 v[0:1], 8, v[0:1]
	v_lshl_add_u64 v[0:1], s[4:5], 0, v[0:1]
	v_lshlrev_b32_e32 v128, 4, v68
	v_lshl_add_u64 v[8:9], v[0:1], 0, v[128:129]
	global_load_dwordx4 v[0:3], v[8:9], off
	v_add_co_u32_e32 v10, vcc, s76, v8
	v_mul_i32_i24_e32 v66, 0x12000, v67
	s_nop 0
	v_addc_co_u32_e32 v11, vcc, 0, v9, vcc
	global_load_dwordx4 v[4:7], v[10:11], off
	global_load_dwordx4 v[72:75], v[8:9], off offset:32
	global_load_dwordx4 v[76:79], v[10:11], off offset:32
	global_load_dwordx4 v[80:83], v[8:9], off offset:64
	global_load_dwordx4 v[84:87], v[8:9], off offset:96
	global_load_dwordx4 v[88:91], v[10:11], off offset:64
	global_load_dwordx4 v[92:95], v[10:11], off offset:96
	global_load_dwordx4 v[96:99], v[8:9], off offset:128
	global_load_dwordx4 v[100:103], v[8:9], off offset:160
	global_load_dwordx4 v[104:107], v[10:11], off offset:128
	global_load_dwordx4 v[108:111], v[10:11], off offset:160
	global_load_dwordx4 v[112:115], v[8:9], off offset:192
	global_load_dwordx4 v[116:119], v[8:9], off offset:224
	global_load_dwordx4 v[120:123], v[10:11], off offset:192
	global_load_dwordx4 v[124:127], v[10:11], off offset:224
	v_and_b32_e32 v8, 0x5f, v71
	v_mul_u32_u24_e32 v8, 0x110, v8
	v_add3_u32 v65, v66, v8, v128
	s_waitcnt lgkmcnt(0)
	s_barrier
	ds_read_b128 v[8:11], v65 offset:32768
	ds_read_b128 v[130:133], v65 offset:32800
	s_waitcnt vmcnt(15) lgkmcnt(1)
	v_mfma_f32_32x32x16_bf16 v[32:47], v[0:3], v[8:11], 0
	ds_read_b128 v[12:15], v65 offset:41472
	ds_read_b128 v[136:139], v65 offset:41504
	v_lshlrev_b32_e32 v69, 1, v69
	s_waitcnt vmcnt(14)
	v_mfma_f32_32x32x16_bf16 v[48:63], v[4:7], v[8:11], 0
	s_waitcnt lgkmcnt(1)
	v_mfma_f32_32x32x16_bf16 v[16:31], v[0:3], v[12:15], 0
	v_mfma_f32_32x32x16_bf16 v[0:15], v[4:7], v[12:15], 0
	s_waitcnt vmcnt(13)
	v_mfma_f32_32x32x16_bf16 v[32:47], v[72:75], v[130:133], v[32:47]
	s_waitcnt vmcnt(12)
	v_mfma_f32_32x32x16_bf16 v[48:63], v[76:79], v[130:133], v[48:63]
	s_waitcnt lgkmcnt(0)
	v_mfma_f32_32x32x16_bf16 v[16:31], v[72:75], v[136:139], v[16:31]
	v_mfma_f32_32x32x16_bf16 v[0:15], v[76:79], v[136:139], v[0:15]
	ds_read_b128 v[72:75], v65 offset:32832
	ds_read_b128 v[76:79], v65 offset:32864
	ds_read_b128 v[130:133], v65 offset:41536
	ds_read_b128 v[136:139], v65 offset:41568
	s_waitcnt vmcnt(11) lgkmcnt(3)
	v_mfma_f32_32x32x16_bf16 v[32:47], v[80:83], v[72:75], v[32:47]
	s_waitcnt vmcnt(9)
	v_mfma_f32_32x32x16_bf16 v[48:63], v[88:91], v[72:75], v[48:63]
	s_waitcnt lgkmcnt(1)
	v_mfma_f32_32x32x16_bf16 v[16:31], v[80:83], v[130:133], v[16:31]
	v_mfma_f32_32x32x16_bf16 v[0:15], v[88:91], v[130:133], v[0:15]
	v_mfma_f32_32x32x16_bf16 v[32:47], v[84:87], v[76:79], v[32:47]
	s_waitcnt vmcnt(8)
	v_mfma_f32_32x32x16_bf16 v[48:63], v[92:95], v[76:79], v[48:63]
	ds_read_b128 v[72:75], v65 offset:32896
	ds_read_b128 v[76:79], v65 offset:32928
	s_waitcnt lgkmcnt(2)
	v_mfma_f32_32x32x16_bf16 v[16:31], v[84:87], v[136:139], v[16:31]
	ds_read_b128 v[80:83], v65 offset:41600
	ds_read_b128 v[84:87], v65 offset:41632
	v_mfma_f32_32x32x16_bf16 v[0:15], v[92:95], v[136:139], v[0:15]
	s_waitcnt vmcnt(7) lgkmcnt(3)
	v_mfma_f32_32x32x16_bf16 v[32:47], v[96:99], v[72:75], v[32:47]
	s_waitcnt vmcnt(5)
	v_mfma_f32_32x32x16_bf16 v[48:63], v[104:107], v[72:75], v[48:63]
	s_waitcnt lgkmcnt(1)
	v_mfma_f32_32x32x16_bf16 v[16:31], v[96:99], v[80:83], v[16:31]
	v_mfma_f32_32x32x16_bf16 v[0:15], v[104:107], v[80:83], v[0:15]
	v_mfma_f32_32x32x16_bf16 v[32:47], v[100:103], v[76:79], v[32:47]
	s_waitcnt vmcnt(4)
	v_mfma_f32_32x32x16_bf16 v[48:63], v[108:111], v[76:79], v[48:63]
	ds_read_b128 v[72:75], v65 offset:32960
	ds_read_b128 v[76:79], v65 offset:32992
	s_waitcnt lgkmcnt(2)
	v_mfma_f32_32x32x16_bf16 v[16:31], v[100:103], v[84:87], v[16:31]
	v_mfma_f32_32x32x16_bf16 v[0:15], v[108:111], v[84:87], v[0:15]
	ds_read_b128 v[80:83], v65 offset:41664
	ds_read_b128 v[84:87], v65 offset:41696
	v_and_b32_e32 v65, 0xff, v71
	v_cmp_gt_u32_e32 vcc, s77, v65
	s_waitcnt vmcnt(3) lgkmcnt(3)
	v_mfma_f32_32x32x16_bf16 v[32:47], v[112:115], v[72:75], v[32:47]
	s_waitcnt vmcnt(1)
	v_mfma_f32_32x32x16_bf16 v[48:63], v[120:123], v[72:75], v[48:63]
	v_lshlrev_b32_e32 v72, 2, v68
	s_waitcnt lgkmcnt(1)
	v_mfma_f32_32x32x16_bf16 v[16:31], v[112:115], v[80:83], v[16:31]
	v_mfma_f32_32x32x16_bf16 v[0:15], v[120:123], v[80:83], v[0:15]
	v_mfma_f32_32x32x16_bf16 v[32:47], v[116:119], v[76:79], v[32:47]
	s_waitcnt vmcnt(0)
	v_mfma_f32_32x32x16_bf16 v[48:63], v[124:127], v[76:79], v[48:63]
	s_nop 9
	s_waitcnt lgkmcnt(0)
	v_mfma_f32_32x32x16_bf16 v[16:31], v[116:119], v[84:87], v[16:31]
	v_mfma_f32_32x32x16_bf16 v[0:15], v[124:127], v[84:87], v[0:15]
	v_and_b32_e32 v32, s86, v32
	v_and_b32_e32 v33, s86, v33
	v_and_b32_e32 v34, s86, v34
	v_and_b32_e32 v35, s86, v35
	v_and_b32_e32 v36, s86, v36
	v_and_b32_e32 v37, s86, v37
	v_and_b32_e32 v38, s86, v38
	v_and_b32_e32 v39, s86, v39
	v_and_b32_e32 v40, s86, v40
	v_and_b32_e32 v41, s86, v41
	v_and_b32_e32 v42, s86, v42
	v_and_b32_e32 v43, s86, v43
	v_and_b32_e32 v44, s86, v44
	v_and_b32_e32 v45, s86, v45
	v_and_b32_e32 v46, s86, v46
	v_and_b32_e32 v47, s86, v47
	v_or_b32_e32 v73, 1, v72
	v_or_b32_e32 v74, 2, v72
	v_or_b32_e32 v75, 3, v72
	v_or_b32_e32 v76, 8, v72
	v_or_b32_e32 v77, 9, v72
	v_or_b32_e32 v78, 10, v72
	v_or_b32_e32 v79, 11, v72
	v_or_b32_e32 v80, 16, v72
	v_or_b32_e32 v81, 17, v72
	v_or_b32_e32 v82, 18, v72
	v_or_b32_e32 v83, 19, v72
	v_or_b32_e32 v84, 24, v72
	v_or_b32_e32 v85, 25, v72
	v_or_b32_e32 v86, 26, v72
	v_or_b32_e32 v87, 27, v72
	v_and_or_b32 v48, v48, s86, v72
	v_and_or_b32 v49, v49, s86, v73
	v_and_or_b32 v50, v50, s86, v74
	v_and_or_b32 v51, v51, s86, v75
	v_and_or_b32 v52, v52, s86, v76
	v_and_or_b32 v53, v53, s86, v77
	v_and_or_b32 v54, v54, s86, v78
	v_and_or_b32 v55, v55, s86, v79
	v_and_or_b32 v56, v56, s86, v80
	v_and_or_b32 v57, v57, s86, v81
	v_and_or_b32 v58, v58, s86, v82
	v_and_or_b32 v59, v59, s86, v83
	v_and_or_b32 v60, v60, s86, v84
	v_and_or_b32 v61, v61, s86, v85
	v_and_or_b32 v62, v62, s86, v86
	v_and_or_b32 v63, v63, s86, v87
	v_or3_b32 v32, v70, v32, v72
	v_or3_b32 v48, v48, v70, 32
	v_or3_b32 v33, v70, v33, v73
	v_or3_b32 v49, v49, v70, 32
	v_or3_b32 v34, v70, v34, v74
	v_or3_b32 v50, v50, v70, 32
	v_or3_b32 v35, v70, v35, v75
	v_or3_b32 v51, v51, v70, 32
	v_or3_b32 v36, v70, v36, v76
	v_or3_b32 v52, v52, v70, 32
	v_or3_b32 v37, v70, v37, v77
	v_or3_b32 v53, v53, v70, 32
	v_or3_b32 v38, v70, v38, v78
	v_or3_b32 v54, v54, v70, 32
	v_or3_b32 v39, v70, v39, v79
	v_or3_b32 v55, v55, v70, 32
	v_or3_b32 v40, v70, v40, v80
	v_or3_b32 v56, v56, v70, 32
	v_or3_b32 v41, v70, v41, v81
	v_or3_b32 v57, v57, v70, 32
	v_or3_b32 v42, v70, v42, v82
	v_or3_b32 v58, v58, v70, 32
	v_or3_b32 v43, v70, v43, v83
	v_or3_b32 v59, v59, v70, 32
	v_or3_b32 v44, v70, v44, v84
	v_or3_b32 v60, v60, v70, 32
	v_or3_b32 v45, v70, v45, v85
	v_or3_b32 v61, v61, v70, 32
	v_or3_b32 v46, v70, v46, v86
	v_or3_b32 v62, v62, v70, 32
	v_or3_b32 v47, v70, v47, v87
	v_or3_b32 v63, v63, v70, 32
	v_max_f32_e32 v88, v32, v45
	v_min_f32_e32 v32, v32, v45
	v_max_f32_e32 v45, v33, v44
	v_min_f32_e32 v33, v33, v44
	v_max_f32_e32 v44, v34, v47
	v_min_f32_e32 v34, v34, v47
	v_max_f32_e32 v47, v35, v46
	v_min_f32_e32 v35, v35, v46
	v_max_f32_e32 v46, v36, v40
	v_min_f32_e32 v36, v36, v40
	v_max_f32_e32 v40, v37, v38
	v_min_f32_e32 v37, v37, v38
	v_max_f32_e32 v38, v39, v43
	v_min_f32_e32 v39, v39, v43
	v_max_f32_e32 v43, v41, v42
	v_min_f32_e32 v41, v41, v42
	v_max_f32_e32 v96, v48, v61
	v_min_f32_e32 v48, v48, v61
	v_max_f32_e32 v61, v49, v60
	v_min_f32_e32 v49, v49, v60
	v_max_f32_e32 v60, v50, v63
	v_min_f32_e32 v50, v50, v63
	v_max_f32_e32 v63, v51, v62
	v_min_f32_e32 v51, v51, v62
	v_max_f32_e32 v62, v52, v56
	v_min_f32_e32 v52, v52, v56
	v_max_f32_e32 v56, v53, v54
	v_min_f32_e32 v53, v53, v54
	v_max_f32_e32 v54, v55, v59
	v_min_f32_e32 v55, v55, v59
	v_max_f32_e32 v59, v57, v58
	v_min_f32_e32 v57, v57, v58
	v_max_f32_e32 v42, v88, v40
	v_min_f32_e32 v40, v88, v40
	v_max_f32_e32 v88, v45, v38
	v_min_f32_e32 v38, v45, v38
	v_max_f32_e32 v45, v44, v43
	v_min_f32_e32 v43, v44, v43
	v_max_f32_e32 v44, v47, v46
	v_min_f32_e32 v46, v47, v46
	v_max_f32_e32 v47, v37, v32
	v_min_f32_e32 v32, v37, v32
	v_max_f32_e32 v37, v36, v35
	v_min_f32_e32 v35, v36, v35
	v_max_f32_e32 v36, v41, v34
	v_min_f32_e32 v34, v41, v34
	v_max_f32_e32 v41, v39, v33
	v_min_f32_e32 v33, v39, v33
	v_max_f32_e32 v58, v96, v56
	v_min_f32_e32 v56, v96, v56
	v_max_f32_e32 v96, v61, v54
	v_min_f32_e32 v54, v61, v54
	v_max_f32_e32 v61, v60, v59
	v_min_f32_e32 v59, v60, v59
	v_max_f32_e32 v60, v63, v62
	v_min_f32_e32 v62, v63, v62
	v_max_f32_e32 v63, v53, v48
	v_min_f32_e32 v48, v53, v48
	v_max_f32_e32 v53, v52, v51
	v_min_f32_e32 v51, v52, v51
	v_max_f32_e32 v52, v57, v50
	v_min_f32_e32 v50, v57, v50
	v_max_f32_e32 v57, v55, v49
	v_min_f32_e32 v49, v55, v49
	v_max_f32_e32 v39, v42, v88
	v_min_f32_e32 v42, v42, v88
	v_max_f32_e32 v88, v45, v44
	v_min_f32_e32 v44, v45, v44
	v_max_f32_e32 v45, v46, v40
	v_min_f32_e32 v40, v46, v40
	v_max_f32_e32 v46, v47, v37
	v_min_f32_e32 v37, v47, v37
	v_max_f32_e32 v47, v38, v43
	v_min_f32_e32 v38, v38, v43
	v_max_f32_e32 v43, v36, v41
	v_min_f32_e32 v36, v36, v41
	v_max_f32_e32 v41, v33, v32
	v_min_f32_e32 v32, v33, v32
	v_max_f32_e32 v33, v35, v34
	v_min_f32_e32 v34, v35, v34
	v_max_f32_e32 v55, v58, v96
	v_min_f32_e32 v58, v58, v96
	v_max_f32_e32 v96, v61, v60
	v_min_f32_e32 v60, v61, v60
	v_max_f32_e32 v61, v62, v56
	v_min_f32_e32 v56, v62, v56
	v_max_f32_e32 v62, v63, v53
	v_min_f32_e32 v53, v63, v53
	v_max_f32_e32 v63, v54, v59
	v_min_f32_e32 v54, v54, v59
	v_max_f32_e32 v59, v52, v57
	v_min_f32_e32 v52, v52, v57
	v_max_f32_e32 v57, v49, v48
	v_min_f32_e32 v48, v49, v48
	v_max_f32_e32 v49, v51, v50
	v_min_f32_e32 v50, v51, v50
	v_min_f32_e32 v35, v39, v88
	v_max_f32_e32 v89, v42, v44
	v_min_f32_e32 v42, v42, v44
	v_max_f32_e32 v44, v45, v43
	v_min_f32_e32 v43, v45, v43
	v_max_f32_e32 v45, v40, v36
	v_min_f32_e32 v36, v40, v36
	v_max_f32_e32 v40, v46, v47
	v_min_f32_e32 v46, v46, v47
	v_max_f32_e32 v47, v37, v38
	v_min_f32_e32 v37, v37, v38
	v_max_f32_e32 v38, v41, v33
	v_min_f32_e32 v33, v41, v33
	v_max_f32_e32 v41, v32, v34
	v_min_f32_e32 v51, v55, v96
	v_max_f32_e32 v97, v58, v60
	v_min_f32_e32 v58, v58, v60
	v_max_f32_e32 v60, v61, v59
	v_min_f32_e32 v59, v61, v59
	v_max_f32_e32 v61, v56, v52
	v_min_f32_e32 v52, v56, v52
	v_max_f32_e32 v56, v62, v63
	v_min_f32_e32 v62, v62, v63
	v_max_f32_e32 v63, v53, v54
	v_min_f32_e32 v53, v53, v54
	v_max_f32_e32 v54, v57, v49
	v_min_f32_e32 v49, v57, v49
	v_max_f32_e32 v57, v48, v50
	v_min_f32_e32 v32, v32, v34
	v_max_f32_e32 v34, v89, v35
	v_min_f32_e32 v35, v89, v35
	v_max_f32_e32 v89, v42, v38
	v_min_f32_e32 v38, v42, v38
	v_max_f32_e32 v42, v44, v40
	v_min_f32_e32 v40, v44, v40
	v_max_f32_e32 v44, v45, v46
	v_min_f32_e32 v45, v45, v46
	v_max_f32_e32 v46, v47, v43
	v_min_f32_e32 v43, v47, v43
	v_max_f32_e32 v47, v37, v36
	v_min_f32_e32 v36, v37, v36
	v_max_f32_e32 v37, v41, v33
	v_min_f32_e32 v48, v48, v50
	v_max_f32_e32 v50, v97, v51
	v_min_f32_e32 v51, v97, v51
	v_max_f32_e32 v97, v58, v54
	v_min_f32_e32 v54, v58, v54
	v_max_f32_e32 v58, v60, v56
	v_min_f32_e32 v56, v60, v56
	v_max_f32_e32 v60, v61, v62
	v_min_f32_e32 v61, v61, v62
	v_max_f32_e32 v62, v63, v59
	v_min_f32_e32 v59, v63, v59
	v_max_f32_e32 v63, v53, v52
	v_min_f32_e32 v52, v53, v52
	v_max_f32_e32 v53, v57, v49
	v_min_f32_e32 v33, v41, v33
	v_max_f32_e32 v90, v35, v40
	v_min_f32_e32 v35, v35, v40
	v_max_f32_e32 v40, v44, v46
	v_min_f32_e32 v44, v44, v46
	v_max_f32_e32 v46, v45, v43
	v_min_f32_e32 v43, v45, v43
	v_max_f32_e32 v45, v47, v37
	v_min_f32_e32 v49, v57, v49
	v_max_f32_e32 v98, v51, v56
	v_min_f32_e32 v51, v51, v56
	v_max_f32_e32 v56, v60, v62
	v_min_f32_e32 v60, v60, v62
	v_max_f32_e32 v62, v61, v59
	v_min_f32_e32 v59, v61, v59
	v_max_f32_e32 v61, v63, v53
	v_min_f32_e32 v37, v47, v37
	v_max_f32_e32 v47, v36, v33
	v_max_f32_e32 v91, v89, v35
	v_min_f32_e32 v35, v89, v35
	v_max_f32_e32 v89, v45, v38
	v_min_f32_e32 v38, v45, v38
	v_min_f32_e32 v53, v63, v53
	v_max_f32_e32 v63, v52, v49
	v_max_f32_e32 v99, v97, v51
	v_min_f32_e32 v51, v97, v51
	v_max_f32_e32 v97, v61, v54
	v_min_f32_e32 v54, v61, v54
	v_min_f32_e32 v41, v34, v42
	v_max_f32_e32 v45, v47, v37
	v_min_f32_e32 v37, v47, v37
	v_max_f32_e32 v47, v91, v40
	v_min_f32_e32 v40, v91, v40
	v_max_f32_e32 v91, v35, v44
	v_min_f32_e32 v35, v35, v44
	v_max_f32_e32 v44, v46, v89
	v_min_f32_e32 v46, v46, v89
	v_max_f32_e32 v89, v43, v38
	v_min_f32_e32 v57, v50, v58
	v_max_f32_e32 v61, v63, v53
	v_min_f32_e32 v53, v63, v53
	v_max_f32_e32 v63, v99, v56
	v_min_f32_e32 v56, v99, v56
	v_max_f32_e32 v99, v51, v60
	v_min_f32_e32 v51, v51, v60
	v_max_f32_e32 v60, v62, v97
	v_min_f32_e32 v62, v62, v97
	v_max_f32_e32 v97, v59, v54
	v_min_f32_e32 v33, v36, v33
	v_min_f32_e32 v36, v90, v41
	v_min_f32_e32 v38, v43, v38
	v_min_f32_e32 v92, v40, v91
	v_max_f32_e32 v93, v44, v35
	v_min_f32_e32 v35, v44, v35
	v_max_f32_e32 v44, v46, v89
	v_min_f32_e32 v49, v52, v49
	v_min_f32_e32 v52, v98, v57
	v_min_f32_e32 v54, v59, v54
	v_min_f32_e32 v100, v56, v99
	v_max_f32_e32 v101, v60, v51
	v_min_f32_e32 v51, v60, v51
	v_max_f32_e32 v60, v62, v97
	v_min_f32_e32 v43, v47, v36
	v_min_f32_e32 v46, v46, v89
	v_min_f32_e32 v89, v45, v38
	v_min_f32_e32 v94, v92, v93
	v_min_f32_e32 v95, v35, v44
	v_min_f32_e32 v59, v63, v52
	v_min_f32_e32 v62, v62, v97
	v_min_f32_e32 v97, v61, v54
	v_min_f32_e32 v102, v100, v101
	v_min_f32_e32 v103, v51, v60
	v_max3_f32 v39, v39, v88, v48
	v_max3_f32 v34, v34, v42, v49
	v_max3_f32 v41, v90, v41, v53
	v_max3_f32 v36, v47, v36, v97
	v_max3_f32 v42, v43, v61, v54
	v_max3_f32 v40, v40, v91, v62
	v_max3_f32 v43, v92, v93, v103
	v_max3_f32 v47, v94, v51, v60
	v_max3_f32 v35, v35, v44, v102
	v_max3_f32 v44, v95, v100, v101
	v_max3_f32 v46, v46, v56, v99
	v_max3_f32 v38, v45, v38, v59
	v_max3_f32 v45, v89, v63, v52
	v_max3_f32 v37, v37, v98, v57
	v_max3_f32 v33, v33, v50, v58
	v_max3_f32 v32, v32, v55, v96
	v_max_f32_e32 v48, v39, v35
	v_min_f32_e32 v35, v39, v35
	v_max_f32_e32 v39, v34, v44
	v_min_f32_e32 v34, v34, v44
	v_max_f32_e32 v44, v41, v46
	v_min_f32_e32 v41, v41, v46
	v_max_f32_e32 v46, v36, v38
	v_min_f32_e32 v36, v36, v38
	v_max_f32_e32 v38, v42, v45
	v_min_f32_e32 v42, v42, v45
	v_max_f32_e32 v45, v40, v37
	v_min_f32_e32 v37, v40, v37
	v_max_f32_e32 v40, v43, v33
	v_min_f32_e32 v33, v43, v33
	v_max_f32_e32 v43, v47, v32
	v_min_f32_e32 v32, v47, v32
	v_max_f32_e32 v47, v48, v38
	v_min_f32_e32 v38, v48, v38
	v_max_f32_e32 v48, v39, v45
	v_min_f32_e32 v39, v39, v45
	v_max_f32_e32 v45, v44, v40
	v_min_f32_e32 v40, v44, v40
	v_max_f32_e32 v44, v46, v43
	v_min_f32_e32 v43, v46, v43
	v_max_f32_e32 v46, v35, v42
	v_min_f32_e32 v35, v35, v42
	v_max_f32_e32 v42, v34, v37
	v_min_f32_e32 v34, v34, v37
	v_max_f32_e32 v37, v41, v33
	v_min_f32_e32 v33, v41, v33
	v_max_f32_e32 v41, v36, v32
	v_min_f32_e32 v32, v36, v32
	v_max_f32_e32 v36, v47, v45
	v_min_f32_e32 v45, v47, v45
	v_max_f32_e32 v47, v48, v44
	v_min_f32_e32 v44, v48, v44
	v_max_f32_e32 v48, v38, v40
	v_min_f32_e32 v40, v38, v40
	v_max_f32_e32 v38, v39, v43
	v_min_f32_e32 v39, v39, v43
	v_max_f32_e32 v43, v46, v37
	v_min_f32_e32 v46, v46, v37
	v_max_f32_e32 v51, v35, v33
	v_min_f32_e32 v52, v35, v33
	v_max_f32_e32 v53, v34, v32
	v_min_f32_e32 v54, v34, v32
	v_max_f32_e32 v32, v36, v47
	v_min_f32_e32 v33, v36, v47
	v_max_f32_e32 v36, v48, v38
	v_min_f32_e32 v37, v48, v38
	v_lshlrev_b32_e32 v48, 2, v71
	v_max_f32_e32 v49, v42, v41
	v_and_b32_e32 v48, 0x17c, v48
	v_min_f32_e32 v50, v42, v41
	v_max_f32_e32 v38, v40, v39
	v_min_f32_e32 v39, v40, v39
	v_max_f32_e32 v40, v43, v49
	v_min_f32_e32 v41, v43, v49
	v_or3_b32 v49, v69, v48, v68
	v_lshlrev_b32_e32 v49, 6, v49
	v_max_f32_e32 v34, v45, v44
	v_min_f32_e32 v35, v45, v44
	v_mad_i32_i24 v49, v67, s75, v49
	v_max_f32_e32 v42, v46, v50
	v_min_f32_e32 v43, v46, v50
	v_max_f32_e32 v44, v51, v53
	v_min_f32_e32 v45, v51, v53
	v_max_f32_e32 v46, v52, v54
	v_min_f32_e32 v47, v52, v54
	v_bfe_u32 v240, v49, 8, 4
	v_lshlrev_b32_e32 v240, 4, v240
	v_xor_b32_e32 v240, v49, v240
	ds_write_b128 v240, v[32:35]
	v_xor_b32_e32 v241, 16, v240
	ds_write_b128 v241, v[36:39]
	v_xor_b32_e32 v241, 32, v240
	ds_write_b128 v241, v[40:43]
	v_xor_b32_e32 v241, 48, v240
	ds_write_b128 v241, v[44:47]
	v_and_b32_e32 v16, s86, v16
	v_and_b32_e32 v17, s86, v17
	v_and_b32_e32 v18, s86, v18
	v_and_b32_e32 v19, s86, v19
	v_and_b32_e32 v20, s86, v20
	v_and_b32_e32 v21, s86, v21
	v_and_b32_e32 v22, s86, v22
	v_and_b32_e32 v23, s86, v23
	v_and_b32_e32 v24, s86, v24
	v_and_b32_e32 v25, s86, v25
	v_and_b32_e32 v26, s86, v26
	v_and_b32_e32 v27, s86, v27
	v_and_b32_e32 v28, s86, v28
	v_and_b32_e32 v29, s86, v29
	v_and_b32_e32 v30, s86, v30
	v_and_b32_e32 v31, s86, v31
	v_and_or_b32 v0, v0, s86, v72
	v_and_or_b32 v1, v1, s86, v73
	v_and_or_b32 v2, v2, s86, v74
	v_and_or_b32 v3, v3, s86, v75
	v_and_or_b32 v4, v4, s86, v76
	v_and_or_b32 v5, v5, s86, v77
	v_and_or_b32 v6, v6, s86, v78
	v_and_or_b32 v7, v7, s86, v79
	v_and_or_b32 v8, v8, s86, v80
	v_and_or_b32 v9, v9, s86, v81
	v_and_or_b32 v10, v10, s86, v82
	v_and_or_b32 v11, v11, s86, v83
	v_and_or_b32 v12, v12, s86, v84
	v_and_or_b32 v13, v13, s86, v85
	v_and_or_b32 v14, v14, s86, v86
	v_and_or_b32 v15, v15, s86, v87
	v_or3_b32 v16, v70, v16, v72
	v_or3_b32 v0, v0, v70, 32
	v_or3_b32 v17, v70, v17, v73
	v_or3_b32 v1, v1, v70, 32
	v_or3_b32 v18, v70, v18, v74
	v_or3_b32 v2, v2, v70, 32
	v_or3_b32 v19, v70, v19, v75
	v_or3_b32 v3, v3, v70, 32
	v_or3_b32 v20, v70, v20, v76
	v_or3_b32 v4, v4, v70, 32
	v_or3_b32 v21, v70, v21, v77
	v_or3_b32 v5, v5, v70, 32
	v_or3_b32 v22, v70, v22, v78
	v_or3_b32 v6, v6, v70, 32
	v_or3_b32 v23, v70, v23, v79
	v_or3_b32 v7, v7, v70, 32
	v_or3_b32 v24, v70, v24, v80
	v_or3_b32 v8, v8, v70, 32
	v_or3_b32 v25, v70, v25, v81
	v_or3_b32 v9, v9, v70, 32
	v_or3_b32 v26, v70, v26, v82
	v_or3_b32 v10, v10, v70, 32
	v_or3_b32 v27, v70, v27, v83
	v_or3_b32 v11, v11, v70, 32
	v_or3_b32 v28, v70, v28, v84
	v_or3_b32 v12, v12, v70, 32
	v_or3_b32 v29, v70, v29, v85
	v_or3_b32 v13, v13, v70, 32
	v_or3_b32 v30, v70, v30, v86
	v_or3_b32 v14, v14, v70, 32
	v_or3_b32 v31, v70, v31, v87
	v_or3_b32 v15, v15, v70, 32
	v_max_f32_e32 v32, v16, v29
	v_min_f32_e32 v16, v16, v29
	v_max_f32_e32 v29, v17, v28
	v_min_f32_e32 v17, v17, v28
	v_max_f32_e32 v28, v18, v31
	v_min_f32_e32 v18, v18, v31
	v_max_f32_e32 v31, v19, v30
	v_min_f32_e32 v19, v19, v30
	v_max_f32_e32 v30, v20, v24
	v_min_f32_e32 v20, v20, v24
	v_max_f32_e32 v24, v21, v22
	v_min_f32_e32 v21, v21, v22
	v_max_f32_e32 v22, v23, v27
	v_min_f32_e32 v23, v23, v27
	v_max_f32_e32 v27, v25, v26
	v_min_f32_e32 v25, v25, v26
	v_max_f32_e32 v40, v0, v13
	v_min_f32_e32 v0, v0, v13
	v_max_f32_e32 v13, v1, v12
	v_min_f32_e32 v1, v1, v12
	v_max_f32_e32 v12, v2, v15
	v_min_f32_e32 v2, v2, v15
	v_max_f32_e32 v15, v3, v14
	v_min_f32_e32 v3, v3, v14
	v_max_f32_e32 v14, v4, v8
	v_min_f32_e32 v4, v4, v8
	v_max_f32_e32 v8, v5, v6
	v_min_f32_e32 v5, v5, v6
	v_max_f32_e32 v6, v7, v11
	v_min_f32_e32 v7, v7, v11
	v_max_f32_e32 v11, v9, v10
	v_min_f32_e32 v9, v9, v10
	v_max_f32_e32 v26, v32, v24
	v_min_f32_e32 v24, v32, v24
	v_max_f32_e32 v32, v29, v22
	v_min_f32_e32 v22, v29, v22
	v_max_f32_e32 v29, v28, v27
	v_min_f32_e32 v27, v28, v27
	v_max_f32_e32 v28, v31, v30
	v_min_f32_e32 v30, v31, v30
	v_max_f32_e32 v31, v21, v16
	v_min_f32_e32 v16, v21, v16
	v_max_f32_e32 v21, v20, v19
	v_min_f32_e32 v19, v20, v19
	v_max_f32_e32 v20, v25, v18
	v_min_f32_e32 v18, v25, v18
	v_max_f32_e32 v25, v23, v17
	v_min_f32_e32 v17, v23, v17
	v_max_f32_e32 v10, v40, v8
	v_min_f32_e32 v8, v40, v8
	v_max_f32_e32 v40, v13, v6
	v_min_f32_e32 v6, v13, v6
	v_max_f32_e32 v13, v12, v11
	v_min_f32_e32 v11, v12, v11
	v_max_f32_e32 v12, v15, v14
	v_min_f32_e32 v14, v15, v14
	v_max_f32_e32 v15, v5, v0
	v_min_f32_e32 v0, v5, v0
	v_max_f32_e32 v5, v4, v3
	v_min_f32_e32 v3, v4, v3
	v_max_f32_e32 v4, v9, v2
	v_min_f32_e32 v2, v9, v2
	v_max_f32_e32 v9, v7, v1
	v_min_f32_e32 v1, v7, v1
	v_max_f32_e32 v23, v26, v32
	v_min_f32_e32 v26, v26, v32
	v_max_f32_e32 v32, v29, v28
	v_min_f32_e32 v28, v29, v28
	v_max_f32_e32 v29, v30, v24
	v_min_f32_e32 v24, v30, v24
	v_max_f32_e32 v30, v31, v21
	v_min_f32_e32 v21, v31, v21
	v_max_f32_e32 v31, v22, v27
	v_min_f32_e32 v22, v22, v27
	v_max_f32_e32 v27, v20, v25
	v_min_f32_e32 v20, v20, v25
	v_max_f32_e32 v25, v17, v16
	v_min_f32_e32 v16, v17, v16
	v_max_f32_e32 v17, v19, v18
	v_min_f32_e32 v18, v19, v18
	v_max_f32_e32 v7, v10, v40
	v_min_f32_e32 v10, v10, v40
	v_max_f32_e32 v40, v13, v12
	v_min_f32_e32 v12, v13, v12
	v_max_f32_e32 v13, v14, v8
	v_min_f32_e32 v8, v14, v8
	v_max_f32_e32 v14, v15, v5
	v_min_f32_e32 v5, v15, v5
	v_max_f32_e32 v15, v6, v11
	v_min_f32_e32 v6, v6, v11
	v_max_f32_e32 v11, v4, v9
	v_min_f32_e32 v4, v4, v9
	v_max_f32_e32 v9, v1, v0
	v_min_f32_e32 v0, v1, v0
	v_max_f32_e32 v1, v3, v2
	v_min_f32_e32 v2, v3, v2
	v_min_f32_e32 v19, v23, v32
	v_max_f32_e32 v33, v26, v28
	v_min_f32_e32 v26, v26, v28
	v_max_f32_e32 v28, v29, v27
	v_min_f32_e32 v27, v29, v27
	v_max_f32_e32 v29, v24, v20
	v_min_f32_e32 v20, v24, v20
	v_max_f32_e32 v24, v30, v31
	v_min_f32_e32 v30, v30, v31
	v_max_f32_e32 v31, v21, v22
	v_min_f32_e32 v21, v21, v22
	v_max_f32_e32 v22, v25, v17
	v_min_f32_e32 v17, v25, v17
	v_max_f32_e32 v25, v16, v18
	v_min_f32_e32 v3, v7, v40
	v_max_f32_e32 v41, v10, v12
	v_min_f32_e32 v10, v10, v12
	v_max_f32_e32 v12, v13, v11
	v_min_f32_e32 v11, v13, v11
	v_max_f32_e32 v13, v8, v4
	v_min_f32_e32 v4, v8, v4
	v_max_f32_e32 v8, v14, v15
	v_min_f32_e32 v14, v14, v15
	v_max_f32_e32 v15, v5, v6
	v_min_f32_e32 v5, v5, v6
	v_max_f32_e32 v6, v9, v1
	v_min_f32_e32 v1, v9, v1
	v_max_f32_e32 v9, v0, v2
	v_min_f32_e32 v16, v16, v18
	v_max_f32_e32 v18, v33, v19
	v_min_f32_e32 v19, v33, v19
	v_max_f32_e32 v33, v26, v22
	v_min_f32_e32 v22, v26, v22
	v_max_f32_e32 v26, v28, v24
	v_min_f32_e32 v24, v28, v24
	v_max_f32_e32 v28, v29, v30
	v_min_f32_e32 v29, v29, v30
	v_max_f32_e32 v30, v31, v27
	v_min_f32_e32 v27, v31, v27
	v_max_f32_e32 v31, v21, v20
	v_min_f32_e32 v20, v21, v20
	v_max_f32_e32 v21, v25, v17
	v_min_f32_e32 v0, v0, v2
	v_max_f32_e32 v2, v41, v3
	v_min_f32_e32 v3, v41, v3
	v_max_f32_e32 v41, v10, v6
	v_min_f32_e32 v6, v10, v6
	v_max_f32_e32 v10, v12, v8
	v_min_f32_e32 v8, v12, v8
	v_max_f32_e32 v12, v13, v14
	v_min_f32_e32 v13, v13, v14
	v_max_f32_e32 v14, v15, v11
	v_min_f32_e32 v11, v15, v11
	v_max_f32_e32 v15, v5, v4
	v_min_f32_e32 v4, v5, v4
	v_max_f32_e32 v5, v9, v1
	v_min_f32_e32 v17, v25, v17
	v_max_f32_e32 v34, v19, v24
	v_min_f32_e32 v19, v19, v24
	v_max_f32_e32 v24, v28, v30
	v_min_f32_e32 v28, v28, v30
	v_max_f32_e32 v30, v29, v27
	v_min_f32_e32 v27, v29, v27
	v_max_f32_e32 v29, v31, v21
	v_min_f32_e32 v1, v9, v1
	v_max_f32_e32 v42, v3, v8
	v_min_f32_e32 v3, v3, v8
	v_max_f32_e32 v8, v12, v14
	v_min_f32_e32 v12, v12, v14
	v_max_f32_e32 v14, v13, v11
	v_min_f32_e32 v11, v13, v11
	v_max_f32_e32 v13, v15, v5
	v_min_f32_e32 v21, v31, v21
	v_max_f32_e32 v31, v20, v17
	v_max_f32_e32 v35, v33, v19
	v_min_f32_e32 v19, v33, v19
	v_max_f32_e32 v33, v29, v22
	v_min_f32_e32 v22, v29, v22
	v_min_f32_e32 v5, v15, v5
	v_max_f32_e32 v15, v4, v1
	v_max_f32_e32 v43, v41, v3
	v_min_f32_e32 v3, v41, v3
	v_max_f32_e32 v41, v13, v6
	v_min_f32_e32 v6, v13, v6
	v_min_f32_e32 v25, v18, v26
	v_max_f32_e32 v29, v31, v21
	v_min_f32_e32 v21, v31, v21
	v_max_f32_e32 v31, v35, v24
	v_min_f32_e32 v24, v35, v24
	v_max_f32_e32 v35, v19, v28
	v_min_f32_e32 v19, v19, v28
	v_max_f32_e32 v28, v30, v33
	v_min_f32_e32 v30, v30, v33
	v_max_f32_e32 v33, v27, v22
	v_min_f32_e32 v9, v2, v10
	v_max_f32_e32 v13, v15, v5
	v_min_f32_e32 v5, v15, v5
	v_max_f32_e32 v15, v43, v8
	v_min_f32_e32 v8, v43, v8
	v_max_f32_e32 v43, v3, v12
	v_min_f32_e32 v3, v3, v12
	v_max_f32_e32 v12, v14, v41
	v_min_f32_e32 v14, v14, v41
	v_max_f32_e32 v41, v11, v6
	v_min_f32_e32 v17, v20, v17
	v_min_f32_e32 v20, v34, v25
	v_min_f32_e32 v22, v27, v22
	v_min_f32_e32 v36, v24, v35
	v_max_f32_e32 v37, v28, v19
	v_min_f32_e32 v19, v28, v19
	v_max_f32_e32 v28, v30, v33
	v_min_f32_e32 v1, v4, v1
	v_min_f32_e32 v4, v42, v9
	v_min_f32_e32 v6, v11, v6
	v_min_f32_e32 v44, v8, v43
	v_max_f32_e32 v45, v12, v3
	v_min_f32_e32 v3, v12, v3
	v_max_f32_e32 v12, v14, v41
	v_min_f32_e32 v27, v31, v20
	v_min_f32_e32 v30, v30, v33
	v_min_f32_e32 v33, v29, v22
	v_min_f32_e32 v38, v36, v37
	v_min_f32_e32 v39, v19, v28
	v_min_f32_e32 v11, v15, v4
	v_min_f32_e32 v14, v14, v41
	v_min_f32_e32 v41, v13, v6
	v_min_f32_e32 v46, v44, v45
	v_min_f32_e32 v47, v3, v12
	v_max3_f32 v0, v23, v32, v0
	v_max3_f32 v1, v18, v26, v1
	v_max3_f32 v5, v34, v25, v5
	v_max3_f32 v18, v31, v20, v41
	v_max3_f32 v6, v27, v13, v6
	v_max3_f32 v13, v24, v35, v14
	v_max3_f32 v14, v36, v37, v47
	v_max3_f32 v3, v38, v3, v12
	v_max3_f32 v12, v19, v28, v46
	v_max3_f32 v19, v39, v44, v45
	v_max3_f32 v8, v30, v8, v43
	v_max3_f32 v11, v29, v22, v11
	v_max3_f32 v4, v33, v15, v4
	v_max3_f32 v9, v21, v42, v9
	v_max3_f32 v2, v17, v2, v10
	v_max3_f32 v7, v16, v7, v40
	v_max_f32_e32 v10, v0, v12
	v_min_f32_e32 v0, v0, v12
	v_max_f32_e32 v12, v1, v19
	v_max_f32_e32 v15, v5, v8
	v_min_f32_e32 v5, v5, v8
	v_max_f32_e32 v8, v18, v11
	v_max_f32_e32 v16, v6, v4
	v_min_f32_e32 v4, v6, v4
	v_max_f32_e32 v6, v13, v9
	v_min_f32_e32 v9, v13, v9
	v_max_f32_e32 v13, v14, v2
	v_min_f32_e32 v2, v14, v2
	v_max_f32_e32 v14, v3, v7
	v_min_f32_e32 v1, v1, v19
	v_min_f32_e32 v11, v18, v11
	v_min_f32_e32 v3, v3, v7
	v_max_f32_e32 v7, v10, v16
	v_min_f32_e32 v10, v10, v16
	v_max_f32_e32 v16, v12, v6
	v_min_f32_e32 v6, v12, v6
	v_max_f32_e32 v12, v15, v13
	v_min_f32_e32 v13, v15, v13
	v_max_f32_e32 v15, v8, v14
	v_min_f32_e32 v8, v8, v14
	v_max_f32_e32 v14, v0, v4
	v_min_f32_e32 v0, v0, v4
	v_max_f32_e32 v4, v1, v9
	v_min_f32_e32 v1, v1, v9
	v_max_f32_e32 v9, v5, v2
	v_min_f32_e32 v2, v5, v2
	v_max_f32_e32 v5, v11, v3
	v_min_f32_e32 v3, v11, v3
	v_max_f32_e32 v11, v7, v12
	v_min_f32_e32 v7, v7, v12
	v_max_f32_e32 v12, v16, v15
	v_min_f32_e32 v15, v16, v15
	v_max_f32_e32 v16, v10, v13
	v_min_f32_e32 v10, v10, v13
	v_max_f32_e32 v13, v6, v8
	v_max_f32_e32 v17, v14, v9
	v_min_f32_e32 v14, v14, v9
	v_max_f32_e32 v9, v4, v5
	v_min_f32_e32 v18, v4, v5
	v_max_f32_e32 v4, v16, v13
	v_min_f32_e32 v5, v16, v13
	v_or3_b32 v16, v68, v48, v69
	v_lshlrev_b32_e32 v16, 6, v16
	v_min_f32_e32 v8, v6, v8
	v_max_f32_e32 v19, v0, v2
	v_min_f32_e32 v20, v0, v2
	v_max_f32_e32 v21, v1, v3
	v_min_f32_e32 v22, v1, v3
	v_max_f32_e32 v0, v11, v12
	v_min_f32_e32 v1, v11, v12
	v_max_f32_e32 v2, v7, v15
	v_min_f32_e32 v3, v7, v15
	v_mad_i32_i24 v16, v67, s75, v16
	v_max_f32_e32 v6, v10, v8
	v_min_f32_e32 v7, v10, v8
	v_max_f32_e32 v8, v17, v9
	v_min_f32_e32 v9, v17, v9
	v_max_f32_e32 v10, v14, v18
	v_min_f32_e32 v11, v14, v18
	v_max_f32_e32 v12, v19, v21
	v_min_f32_e32 v13, v19, v21
	v_max_f32_e32 v14, v20, v22
	v_min_f32_e32 v15, v20, v22
	v_bfe_u32 v240, v16, 8, 4
	v_lshlrev_b32_e32 v240, 4, v240
	v_xor_b32_e32 v240, v16, v240
	ds_write_b128 v240, v[0:3] offset:8192
	v_xor_b32_e32 v241, 16, v240
	ds_write_b128 v241, v[4:7] offset:8192
	v_xor_b32_e32 v241, 32, v240
	ds_write_b128 v241, v[8:11] offset:8192
	v_xor_b32_e32 v241, 48, v240
	ds_write_b128 v241, v[12:15] offset:8192
	s_waitcnt lgkmcnt(0)
	s_barrier
	s_and_saveexec_b64 s[60:61], vcc
	s_cbranch_execz .LBB0_856
	v_lshl_add_u32 v60, v65, 8, v66
	v_bfe_u32 v240, v60, 8, 4
	v_lshlrev_b32_e32 v240, 4, v240
	v_xor_b32_e32 v240, v60, v240
	ds_read_b128 v[0:3], v240
	v_xor_b32_e32 v241, 16, v240
	ds_read_b128 v[4:7], v241
	v_xor_b32_e32 v241, 32, v240
	ds_read_b128 v[8:11], v241
	v_xor_b32_e32 v241, 48, v240
	ds_read_b128 v[12:15], v241
	v_xor_b32_e32 v241, 64, v240
	ds_read_b128 v[16:19], v241
	v_xor_b32_e32 v241, 0x50, v240
	ds_read_b128 v[20:23], v241
	v_xor_b32_e32 v241, 0x80, v240
	ds_read_b128 v[24:27], v241
	v_xor_b32_e32 v241, 0x90, v240
	ds_read_b128 v[28:31], v241
	v_xor_b32_e32 v241, 0xc0, v240
	ds_read_b128 v[32:35], v241
	v_xor_b32_e32 v241, 0xd0, v240
	ds_read_b128 v[36:39], v241
	v_xor_b32_e32 v241, 0x60, v240
	ds_read_b128 v[40:43], v241
	v_xor_b32_e32 v241, 0x70, v240
	ds_read_b128 v[44:47], v241
	v_xor_b32_e32 v241, 0xa0, v240
	ds_read_b128 v[48:51], v241
	v_xor_b32_e32 v241, 0xb0, v240
	ds_read_b128 v[52:55], v241
	v_xor_b32_e32 v241, 0xe0, v240
	ds_read_b128 v[56:59], v241
	v_xor_b32_e32 v241, 0xf0, v240
	ds_read_b128 v[60:63], v241
	s_waitcnt lgkmcnt(4)
	v_max_f32_e32 v0, v0, v47
	v_max_f32_e32 v1, v1, v46
	v_max_f32_e32 v2, v2, v45
	v_max_f32_e32 v3, v3, v44
	v_max_f32_e32 v4, v4, v43
	v_max_f32_e32 v5, v5, v42
	v_max_f32_e32 v6, v6, v41
	v_max_f32_e32 v7, v7, v40
	v_max_f32_e32 v8, v8, v23
	v_max_f32_e32 v9, v9, v22
	v_max_f32_e32 v10, v10, v21
	v_max_f32_e32 v11, v11, v20
	v_max_f32_e32 v12, v12, v19
	v_max_f32_e32 v13, v13, v18
	v_max_f32_e32 v14, v14, v17
	v_max_f32_e32 v15, v15, v16
	s_waitcnt lgkmcnt(0)
	v_max_f32_e32 v24, v24, v63
	v_max_f32_e32 v25, v25, v62
	v_max_f32_e32 v26, v26, v61
	v_max_f32_e32 v27, v27, v60
	v_max_f32_e32 v28, v28, v59
	v_max_f32_e32 v29, v29, v58
	v_max_f32_e32 v30, v30, v57
	v_max_f32_e32 v31, v31, v56
	v_max_f32_e32 v39, v48, v39
	v_max_f32_e32 v38, v49, v38
	v_max_f32_e32 v37, v50, v37
	v_max_f32_e32 v36, v51, v36
	v_max_f32_e32 v35, v52, v35
	v_max_f32_e32 v34, v53, v34
	v_max_f32_e32 v33, v54, v33
	v_max_f32_e32 v32, v55, v32
	v_max_f32_e32 v16, v0, v8
	v_min_f32_e32 v0, v0, v8
	v_max_f32_e32 v8, v1, v9
	v_min_f32_e32 v1, v1, v9
	v_max_f32_e32 v9, v2, v10
	v_min_f32_e32 v2, v2, v10
	v_max_f32_e32 v10, v3, v11
	v_min_f32_e32 v3, v3, v11
	v_max_f32_e32 v11, v4, v12
	v_min_f32_e32 v4, v4, v12
	v_max_f32_e32 v12, v5, v13
	v_min_f32_e32 v5, v5, v13
	v_max_f32_e32 v13, v6, v14
	v_min_f32_e32 v6, v6, v14
	v_max_f32_e32 v14, v7, v15
	v_min_f32_e32 v7, v7, v15
	v_max_f32_e32 v40, v24, v39
	v_min_f32_e32 v24, v24, v39
	v_max_f32_e32 v39, v25, v38
	v_min_f32_e32 v25, v25, v38
	v_max_f32_e32 v38, v26, v37
	v_min_f32_e32 v26, v26, v37
	v_max_f32_e32 v37, v27, v36
	v_min_f32_e32 v27, v27, v36
	v_max_f32_e32 v36, v28, v35
	v_min_f32_e32 v28, v28, v35
	v_max_f32_e32 v35, v29, v34
	v_min_f32_e32 v29, v29, v34
	v_max_f32_e32 v34, v30, v33
	v_min_f32_e32 v30, v30, v33
	v_max_f32_e32 v33, v31, v32
	v_min_f32_e32 v31, v31, v32
	v_max_f32_e32 v15, v16, v11
	v_min_f32_e32 v11, v16, v11
	v_max_f32_e32 v16, v8, v12
	v_min_f32_e32 v8, v8, v12
	v_max_f32_e32 v12, v9, v13
	v_min_f32_e32 v9, v9, v13
	v_max_f32_e32 v13, v10, v14
	v_min_f32_e32 v10, v10, v14
	v_max_f32_e32 v14, v0, v4
	v_min_f32_e32 v0, v0, v4
	v_max_f32_e32 v4, v1, v5
	v_min_f32_e32 v1, v1, v5
	v_max_f32_e32 v5, v2, v6
	v_min_f32_e32 v2, v2, v6
	v_max_f32_e32 v6, v3, v7
	v_min_f32_e32 v3, v3, v7
	v_max_f32_e32 v32, v40, v36
	v_min_f32_e32 v36, v40, v36
	v_max_f32_e32 v40, v39, v35
	v_min_f32_e32 v35, v39, v35
	v_max_f32_e32 v39, v38, v34
	v_min_f32_e32 v34, v38, v34
	v_max_f32_e32 v38, v37, v33
	v_min_f32_e32 v33, v37, v33
	v_max_f32_e32 v37, v24, v28
	v_min_f32_e32 v24, v24, v28
	v_max_f32_e32 v28, v25, v29
	v_min_f32_e32 v25, v25, v29
	v_max_f32_e32 v29, v26, v30
	v_min_f32_e32 v26, v26, v30
	v_max_f32_e32 v30, v27, v31
	v_min_f32_e32 v27, v27, v31
	v_max_f32_e32 v7, v15, v12
	v_min_f32_e32 v12, v15, v12
	v_max_f32_e32 v15, v16, v13
	v_min_f32_e32 v13, v16, v13
	v_max_f32_e32 v16, v11, v9
	v_min_f32_e32 v9, v11, v9
	v_max_f32_e32 v11, v8, v10
	v_min_f32_e32 v8, v8, v10
	v_max_f32_e32 v10, v14, v5
	v_min_f32_e32 v5, v14, v5
	v_max_f32_e32 v14, v4, v6
	v_min_f32_e32 v4, v4, v6
	v_max_f32_e32 v6, v0, v2
	v_min_f32_e32 v0, v0, v2
	v_max_f32_e32 v2, v1, v3
	v_min_f32_e32 v1, v1, v3
	v_max_f32_e32 v31, v32, v39
	v_min_f32_e32 v32, v32, v39
	v_max_f32_e32 v39, v40, v38
	v_min_f32_e32 v38, v40, v38
	v_max_f32_e32 v40, v36, v34
	v_min_f32_e32 v34, v36, v34
	v_max_f32_e32 v36, v35, v33
	v_min_f32_e32 v33, v35, v33
	v_max_f32_e32 v35, v37, v29
	v_min_f32_e32 v29, v37, v29
	v_max_f32_e32 v37, v28, v30
	v_min_f32_e32 v28, v28, v30
	v_max_f32_e32 v30, v24, v26
	v_min_f32_e32 v24, v24, v26
	v_max_f32_e32 v26, v25, v27
	v_min_f32_e32 v25, v25, v27
	v_min_f32_e32 v3, v7, v15
	v_min_f32_e32 v17, v12, v13
	v_min_f32_e32 v18, v16, v11
	v_min_f32_e32 v19, v9, v8
	v_min_f32_e32 v20, v10, v14
	v_min_f32_e32 v21, v5, v4
	v_min_f32_e32 v22, v6, v2
	v_min_f32_e32 v23, v0, v1
	v_min_f32_e32 v27, v31, v39
	v_min_f32_e32 v41, v32, v38
	v_min_f32_e32 v42, v40, v36
	v_min_f32_e32 v43, v34, v33
	v_min_f32_e32 v44, v35, v37
	v_min_f32_e32 v45, v29, v28
	v_min_f32_e32 v46, v30, v26
	v_min_f32_e32 v47, v24, v25
	v_max3_f32 v7, v7, v15, v47
	v_max3_f32 v3, v3, v24, v25
	v_max3_f32 v12, v12, v13, v46
	v_max3_f32 v13, v17, v30, v26
	v_max3_f32 v11, v16, v11, v45
	v_max3_f32 v15, v18, v29, v28
	v_max3_f32 v8, v9, v8, v44
	v_max3_f32 v9, v19, v35, v37
	v_max3_f32 v10, v10, v14, v43
	v_max3_f32 v14, v20, v34, v33
	v_max3_f32 v4, v5, v4, v42
	v_max3_f32 v5, v21, v40, v36
	v_max3_f32 v2, v6, v2, v41
	v_max3_f32 v6, v22, v32, v38
	v_max3_f32 v0, v0, v1, v27
	v_max3_f32 v1, v23, v31, v39
	v_max_f32_e32 v16, v7, v10
	v_min_f32_e32 v7, v7, v10
	v_max_f32_e32 v10, v3, v14
	v_min_f32_e32 v3, v3, v14
	v_max_f32_e32 v14, v12, v4
	v_min_f32_e32 v4, v12, v4
	v_max_f32_e32 v12, v13, v5
	v_min_f32_e32 v5, v13, v5
	v_max_f32_e32 v13, v11, v2
	v_min_f32_e32 v2, v11, v2
	v_max_f32_e32 v11, v15, v6
	v_min_f32_e32 v6, v15, v6
	v_max_f32_e32 v15, v8, v0
	v_min_f32_e32 v0, v8, v0
	v_max_f32_e32 v8, v9, v1
	v_min_f32_e32 v1, v9, v1
	v_max_f32_e32 v9, v16, v13
	v_min_f32_e32 v13, v16, v13
	v_max_f32_e32 v16, v10, v11
	v_min_f32_e32 v10, v10, v11
	v_max_f32_e32 v11, v14, v15
	v_min_f32_e32 v14, v14, v15
	v_max_f32_e32 v15, v12, v8
	v_min_f32_e32 v8, v12, v8
	v_max_f32_e32 v12, v7, v2
	v_min_f32_e32 v2, v7, v2
	v_max_f32_e32 v7, v3, v6
	v_min_f32_e32 v3, v3, v6
	v_max_f32_e32 v6, v4, v0
	v_min_f32_e32 v0, v4, v0
	v_max_f32_e32 v4, v5, v1
	v_min_f32_e32 v1, v5, v1
	v_max_f32_e32 v5, v9, v11
	v_min_f32_e32 v9, v9, v11
	v_max_f32_e32 v11, v16, v15
	v_min_f32_e32 v15, v16, v15
	v_max_f32_e32 v16, v13, v14
	v_min_f32_e32 v13, v13, v14
	v_max_f32_e32 v14, v10, v8
	v_min_f32_e32 v8, v10, v8
	v_max_f32_e32 v10, v12, v6
	v_max_f32_e32 v17, v7, v4
	v_min_f32_e32 v18, v7, v4
	v_max_f32_e32 v19, v2, v0
	v_min_f32_e32 v20, v2, v0
	v_max_f32_e32 v21, v3, v1
	v_min_f32_e32 v22, v3, v1
	v_max_f32_e32 v0, v5, v11
	v_min_f32_e32 v1, v5, v11
	v_max_f32_e32 v4, v16, v14
	v_min_f32_e32 v5, v16, v14
	v_or_b32_e32 v16, s58, v65
	v_min_f32_e32 v12, v12, v6
	v_max_f32_e32 v2, v9, v15
	v_min_f32_e32 v3, v9, v15
	v_max_f32_e32 v6, v13, v8
	v_min_f32_e32 v7, v13, v8
	v_max_f32_e32 v8, v10, v17
	v_min_f32_e32 v9, v10, v17
	v_ashrrev_i32_e32 v17, 31, v16
	v_max_f32_e32 v10, v12, v18
	v_min_f32_e32 v11, v12, v18
	v_lshlrev_b64 v[16:17], 10, v[16:17]
	v_lshlrev_b32_e32 v18, 4, v64
	v_max_f32_e32 v12, v19, v21
	v_min_f32_e32 v13, v19, v21
	v_lshl_add_u64 v[16:17], s[12:13], 0, v[16:17]
	v_ashrrev_i32_e32 v19, 31, v18
	v_lshl_add_u64 v[16:17], v[18:19], 2, v[16:17]
	v_max_f32_e32 v14, v20, v22
	v_min_f32_e32 v15, v20, v22
	v_and_b32_e32 v238, 3, v65
	v_lshl_add_u32 v239, v65, 8, v66
	v_lshl_add_u32 v239, v238, 6, v239
	ds_write_b128 v239, v[0:3]
	ds_write_b128 v239, v[4:7] offset:16
	ds_write_b128 v239, v[8:11] offset:32
	ds_write_b128 v239, v[12:15] offset:48
	v_bfe_u32 v242, v65, 2, 4
	v_and_or_b32 v242, v65, 64, v242
	v_and_b32_e32 v243, 3, v242
	v_lshlrev_b32_e32 v243, 6, v243
	v_lshl_add_u32 v243, v238, 4, v243
	v_lshl_add_u32 v243, v242, 8, v243
	v_add_u32_e32 v243, v66, v243
	ds_read_b128 v[20:23], v243
	ds_read_b128 v[24:27], v243 offset:4096
	ds_read_b128 v[28:31], v243 offset:8192
	ds_read_b128 v[32:35], v243 offset:12288
	v_or_b32_e32 v244, s58, v242
	v_ashrrev_i32_e32 v245, 31, v244
	v_lshlrev_b64 v[244:245], 10, v[244:245]
	v_lshl_add_u64 v[244:245], s[12:13], 0, v[244:245]
	v_lshl_add_u64 v[244:245], v[18:19], 2, v[244:245]
	v_lshlrev_b32_e32 v246, 4, v238
	v_mov_b32_e32 v247, 0
	v_lshl_add_u64 v[244:245], v[244:245], 0, v[246:247]
	v_mov_b32_e32 v246, 0x4000
	s_waitcnt lgkmcnt(3)
	global_store_dwordx4 v[244:245], v[20:23], off
	v_lshl_add_u64 v[244:245], v[244:245], 0, v[246:247]
	s_waitcnt lgkmcnt(2)
	global_store_dwordx4 v[244:245], v[24:27], off
	v_lshl_add_u64 v[244:245], v[244:245], 0, v[246:247]
	s_waitcnt lgkmcnt(1)
	global_store_dwordx4 v[244:245], v[28:31], off
	v_lshl_add_u64 v[244:245], v[244:245], 0, v[246:247]
	s_waitcnt lgkmcnt(0)
	global_store_dwordx4 v[244:245], v[32:35], off
	s_branch .LBB0_856

.LBB0_906:
	s_andn2_saveexec_b64 s[4:5], s[4:5]
	s_cbranch_execz .LBB0_887
	s_lshl_b32 s22, s42, 1
	s_add_i32 s22, s45, s22
	v_lshrrev_b32_e32 v130, 7, v142
	s_ashr_i32 s23, s22, 31
	v_and_b32_e32 v0, 31, v142
	s_lshl_b64 s[24:25], s[22:23], 7
	v_lshlrev_b32_e32 v117, 6, v130
	v_or3_b32 v0, s24, v117, v0
	v_mov_b32_e32 v1, s25
	v_bfe_u32 v118, v142, 5, 1
	v_lshlrev_b64 v[0:1], 8, v[0:1]
	v_lshl_add_u64 v[0:1], s[16:17], 0, v[0:1]
	v_lshlrev_b32_e32 v128, 4, v118
	v_lshl_add_u64 v[8:9], v[0:1], 0, v[128:129]
	global_load_dwordx4 v[0:3], v[8:9], off
	v_add_co_u32_e32 v10, vcc, s37, v8
	v_and_b32_e32 v12, 0x5f, v142
	s_nop 0
	v_addc_co_u32_e32 v11, vcc, 0, v9, vcc
	global_load_dwordx4 v[4:7], v[10:11], off
	global_load_dwordx4 v[120:123], v[8:9], off offset:32
	global_load_dwordx4 v[112:115], v[10:11], off offset:32
	global_load_dwordx4 v[96:99], v[8:9], off offset:64
	global_load_dwordx4 v[108:111], v[10:11], off offset:64
	global_load_dwordx4 v[104:107], v[8:9], off offset:96
	global_load_dwordx4 v[92:95], v[8:9], off offset:128
	global_load_dwordx4 v[84:87], v[8:9], off offset:160
	global_load_dwordx4 v[76:79], v[8:9], off offset:192
	global_load_dwordx4 v[68:71], v[8:9], off offset:224
	global_load_dwordx4 v[100:103], v[10:11], off offset:96
	global_load_dwordx4 v[88:91], v[10:11], off offset:128
	global_load_dwordx4 v[80:83], v[10:11], off offset:160
	global_load_dwordx4 v[72:75], v[10:11], off offset:192
	global_load_dwordx4 v[64:67], v[10:11], off offset:224
	v_mul_u32_u24_e32 v12, 0x110, v12
	v_add3_u32 v131, v143, v12, v128
	s_waitcnt lgkmcnt(0)
	s_barrier
	ds_read_b128 v[8:11], v131 offset:32768
	s_waitcnt vmcnt(16)
	ds_read_b128 v[124:127], v131 offset:32800
	ds_read_b128 v[12:15], v131 offset:41472
	ds_read_b128 v[132:135], v131 offset:41504
	v_lshlrev_b32_e32 v119, 2, v118
	v_or_b32_e32 v128, 17, v119
	v_lshlrev_b32_e32 v130, 1, v130
	v_cmp_gt_u32_e32 vcc, s40, v116
	s_waitcnt vmcnt(14) lgkmcnt(3)
	v_mfma_f32_32x32x16_bf16 v[48:63], v[4:7], v[8:11], 0
	v_mfma_f32_32x32x16_bf16 v[32:47], v[0:3], v[8:11], 0
	s_waitcnt lgkmcnt(1)
	v_mfma_f32_32x32x16_bf16 v[16:31], v[0:3], v[12:15], 0
	s_waitcnt vmcnt(13)
	v_mfma_f32_32x32x16_bf16 v[32:47], v[120:123], v[124:127], v[32:47]
	s_waitcnt vmcnt(12)
	v_mfma_f32_32x32x16_bf16 v[48:63], v[112:115], v[124:127], v[48:63]
	s_waitcnt lgkmcnt(0)
	v_mfma_f32_32x32x16_bf16 v[16:31], v[120:123], v[132:135], v[16:31]
	ds_read_b128 v[120:123], v131 offset:32832
	ds_read_b128 v[124:127], v131 offset:32864
	s_waitcnt vmcnt(11) lgkmcnt(1)
	v_mfma_f32_32x32x16_bf16 v[32:47], v[96:99], v[120:123], v[32:47]
	s_waitcnt vmcnt(10)
	v_mfma_f32_32x32x16_bf16 v[48:63], v[108:111], v[120:123], v[48:63]
	s_waitcnt vmcnt(9) lgkmcnt(0)
	v_mfma_f32_32x32x16_bf16 v[32:47], v[104:107], v[124:127], v[32:47]
	s_waitcnt vmcnt(4)
	v_mfma_f32_32x32x16_bf16 v[48:63], v[100:103], v[124:127], v[48:63]
	ds_read_b128 v[120:123], v131 offset:32896
	ds_read_b128 v[124:127], v131 offset:32928
	v_mfma_f32_32x32x16_bf16 v[0:15], v[4:7], v[12:15], 0
	s_waitcnt lgkmcnt(1)
	v_mfma_f32_32x32x16_bf16 v[32:47], v[92:95], v[120:123], v[32:47]
	s_waitcnt vmcnt(3)
	v_mfma_f32_32x32x16_bf16 v[48:63], v[88:91], v[120:123], v[48:63]
	v_or_b32_e32 v120, 1, v119
	v_or_b32_e32 v121, 2, v119
	v_mfma_f32_32x32x16_bf16 v[0:15], v[112:115], v[132:135], v[0:15]
	s_waitcnt lgkmcnt(0)
	v_mfma_f32_32x32x16_bf16 v[32:47], v[84:87], v[124:127], v[32:47]
	s_waitcnt vmcnt(2)
	v_mfma_f32_32x32x16_bf16 v[48:63], v[80:83], v[124:127], v[48:63]
	ds_read_b128 v[122:125], v131 offset:32960
	ds_read_b128 v[136:139], v131 offset:32992
	ds_read_b128 v[144:147], v131 offset:41536
	ds_read_b128 v[148:151], v131 offset:41568
	ds_read_b128 v[152:155], v131 offset:41600
	ds_read_b128 v[156:159], v131 offset:41632
	ds_read_b128 v[160:163], v131 offset:41664
	ds_read_b128 v[164:167], v131 offset:41696
	v_or_b32_e32 v126, 11, v119
	v_or_b32_e32 v127, 16, v119
	s_waitcnt lgkmcnt(5)
	v_mfma_f32_32x32x16_bf16 v[16:31], v[96:99], v[144:147], v[16:31]
	v_or_b32_e32 v96, 18, v119
	v_mfma_f32_32x32x16_bf16 v[0:15], v[108:111], v[144:147], v[0:15]
	s_waitcnt lgkmcnt(4)
	v_mfma_f32_32x32x16_bf16 v[16:31], v[104:107], v[148:151], v[16:31]
	v_mfma_f32_32x32x16_bf16 v[0:15], v[100:103], v[148:151], v[0:15]
	s_waitcnt lgkmcnt(3)
	v_mfma_f32_32x32x16_bf16 v[16:31], v[92:95], v[152:155], v[16:31]
	v_or_b32_e32 v92, 25, v119
	v_mfma_f32_32x32x16_bf16 v[32:47], v[76:79], v[122:125], v[32:47]
	v_mfma_f32_32x32x16_bf16 v[0:15], v[88:91], v[152:155], v[0:15]
	v_or_b32_e32 v88, 26, v119
	s_waitcnt vmcnt(1)
	v_mfma_f32_32x32x16_bf16 v[48:63], v[72:75], v[122:125], v[48:63]
	v_or_b32_e32 v122, 3, v119
	v_or_b32_e32 v123, 8, v119
	v_or_b32_e32 v124, 9, v119
	v_or_b32_e32 v125, 10, v119
	s_waitcnt lgkmcnt(2)
	v_mfma_f32_32x32x16_bf16 v[16:31], v[84:87], v[156:159], v[16:31]
	v_mfma_f32_32x32x16_bf16 v[32:47], v[68:71], v[136:139], v[32:47]
	v_mfma_f32_32x32x16_bf16 v[0:15], v[80:83], v[156:159], v[0:15]
	s_nop 10
	s_waitcnt vmcnt(0)
	v_mfma_f32_32x32x16_bf16 v[48:63], v[64:67], v[136:139], v[48:63]
	s_waitcnt lgkmcnt(1)
	v_mfma_f32_32x32x16_bf16 v[16:31], v[76:79], v[160:163], v[16:31]
	v_mfma_f32_32x32x16_bf16 v[0:15], v[72:75], v[160:163], v[0:15]
	v_and_b32_e32 v42, s39, v42
	v_and_b32_e32 v43, s39, v43
	v_and_b32_e32 v44, s39, v44
	v_and_b32_e32 v45, s39, v45
	v_or_b32_e32 v97, 19, v119
	v_or_b32_e32 v98, 24, v119
	v_or_b32_e32 v84, 27, v119
	v_and_b32_e32 v32, s39, v32
	v_and_b32_e32 v33, s39, v33
	v_and_b32_e32 v34, s39, v34
	v_and_b32_e32 v35, s39, v35
	v_and_b32_e32 v36, s39, v36
	v_and_b32_e32 v37, s39, v37
	v_and_b32_e32 v38, s39, v38
	v_and_b32_e32 v39, s39, v39
	v_and_b32_e32 v40, s39, v40
	v_and_or_b32 v48, v48, s39, v119
	v_and_or_b32 v49, v49, s39, v120
	v_and_or_b32 v50, v50, s39, v121
	v_and_or_b32 v51, v51, s39, v122
	v_and_or_b32 v52, v52, s39, v123
	v_and_or_b32 v53, v53, s39, v124
	v_and_or_b32 v54, v54, s39, v125
	v_and_or_b32 v55, v55, s39, v126
	v_and_or_b32 v56, v56, s39, v127
	v_and_b32_e32 v41, s39, v41
	v_and_or_b32 v57, v57, s39, v128
	v_and_or_b32 v58, v58, s39, v96
	v_and_or_b32 v59, v59, s39, v97
	v_and_or_b32 v60, v60, s39, v98
	v_and_or_b32 v61, v61, s39, v92
	v_and_b32_e32 v46, s39, v46
	v_and_or_b32 v62, v62, s39, v88
	v_and_b32_e32 v47, s39, v47
	v_and_or_b32 v63, v63, s39, v84
	v_or3_b32 v32, v117, v32, v119
	v_or3_b32 v33, v117, v33, v120
	v_or3_b32 v34, v117, v34, v121
	v_or3_b32 v35, v117, v35, v122
	v_or3_b32 v36, v117, v36, v123
	v_or3_b32 v37, v117, v37, v124
	v_or3_b32 v38, v117, v38, v125
	v_or3_b32 v39, v117, v39, v126
	v_or3_b32 v40, v117, v40, v127
	v_or3_b32 v48, v48, v117, 32
	v_or3_b32 v49, v49, v117, 32
	v_or3_b32 v50, v50, v117, 32
	v_or3_b32 v51, v51, v117, 32
	v_or3_b32 v52, v52, v117, 32
	v_or3_b32 v53, v53, v117, 32
	v_or3_b32 v54, v54, v117, 32
	v_or3_b32 v55, v55, v117, 32
	v_or3_b32 v56, v56, v117, 32
	v_or3_b32 v41, v117, v41, v128
	v_or3_b32 v57, v57, v117, 32
	v_or3_b32 v42, v117, v42, v96
	v_or3_b32 v58, v58, v117, 32
	v_or3_b32 v43, v117, v43, v97
	v_or3_b32 v59, v59, v117, 32
	v_or3_b32 v44, v117, v44, v98
	v_or3_b32 v60, v60, v117, 32
	v_or3_b32 v45, v117, v45, v92
	v_or3_b32 v61, v61, v117, 32
	v_or3_b32 v46, v117, v46, v88
	v_or3_b32 v62, v62, v117, 32
	v_or3_b32 v47, v117, v47, v84
	v_or3_b32 v63, v63, v117, 32
	v_max_f32_e32 v80, v32, v45
	v_min_f32_e32 v32, v32, v45
	v_max_f32_e32 v45, v33, v44
	v_min_f32_e32 v33, v33, v44
	v_max_f32_e32 v44, v34, v47
	v_min_f32_e32 v34, v34, v47
	v_max_f32_e32 v47, v35, v46
	v_min_f32_e32 v35, v35, v46
	v_max_f32_e32 v46, v36, v40
	v_min_f32_e32 v36, v36, v40
	v_max_f32_e32 v40, v37, v38
	v_min_f32_e32 v37, v37, v38
	v_max_f32_e32 v38, v39, v43
	v_min_f32_e32 v39, v39, v43
	v_max_f32_e32 v43, v41, v42
	v_min_f32_e32 v41, v41, v42
	v_max_f32_e32 v72, v48, v61
	v_min_f32_e32 v48, v48, v61
	v_max_f32_e32 v61, v49, v60
	v_min_f32_e32 v49, v49, v60
	v_max_f32_e32 v60, v50, v63
	v_min_f32_e32 v50, v50, v63
	v_max_f32_e32 v63, v51, v62
	v_min_f32_e32 v51, v51, v62
	v_max_f32_e32 v62, v52, v56
	v_min_f32_e32 v52, v52, v56
	v_max_f32_e32 v56, v53, v54
	v_min_f32_e32 v53, v53, v54
	v_max_f32_e32 v54, v55, v59
	v_min_f32_e32 v55, v55, v59
	v_max_f32_e32 v59, v57, v58
	v_min_f32_e32 v57, v57, v58
	s_waitcnt lgkmcnt(0)
	v_mfma_f32_32x32x16_bf16 v[16:31], v[68:71], v[164:167], v[16:31]
	v_max_f32_e32 v42, v80, v40
	v_min_f32_e32 v40, v80, v40
	v_max_f32_e32 v68, v45, v38
	v_min_f32_e32 v38, v45, v38
	v_max_f32_e32 v45, v44, v43
	v_min_f32_e32 v43, v44, v43
	v_max_f32_e32 v44, v47, v46
	v_min_f32_e32 v46, v47, v46
	v_max_f32_e32 v47, v37, v32
	v_min_f32_e32 v32, v37, v32
	v_max_f32_e32 v37, v36, v35
	v_min_f32_e32 v35, v36, v35
	v_max_f32_e32 v36, v41, v34
	v_min_f32_e32 v34, v41, v34
	v_max_f32_e32 v41, v39, v33
	v_min_f32_e32 v33, v39, v33
	v_max_f32_e32 v58, v72, v56
	v_min_f32_e32 v56, v72, v56
	v_max_f32_e32 v72, v61, v54
	v_min_f32_e32 v54, v61, v54
	v_max_f32_e32 v61, v60, v59
	v_min_f32_e32 v59, v60, v59
	v_max_f32_e32 v60, v63, v62
	v_min_f32_e32 v62, v63, v62
	v_max_f32_e32 v63, v53, v48
	v_min_f32_e32 v48, v53, v48
	v_max_f32_e32 v53, v52, v51
	v_min_f32_e32 v51, v52, v51
	v_max_f32_e32 v52, v57, v50
	v_min_f32_e32 v50, v57, v50
	v_max_f32_e32 v57, v55, v49
	v_min_f32_e32 v49, v55, v49
	v_mfma_f32_32x32x16_bf16 v[0:15], v[64:67], v[164:167], v[0:15]
	v_max_f32_e32 v39, v42, v68
	v_min_f32_e32 v42, v42, v68
	v_max_f32_e32 v64, v45, v44
	v_min_f32_e32 v44, v45, v44
	v_max_f32_e32 v45, v46, v40
	v_min_f32_e32 v40, v46, v40
	v_max_f32_e32 v46, v47, v37
	v_min_f32_e32 v37, v47, v37
	v_max_f32_e32 v47, v38, v43
	v_min_f32_e32 v38, v38, v43
	v_max_f32_e32 v43, v36, v41
	v_min_f32_e32 v36, v36, v41
	v_max_f32_e32 v41, v33, v32
	v_min_f32_e32 v32, v33, v32
	v_max_f32_e32 v33, v35, v34
	v_min_f32_e32 v34, v35, v34
	v_max_f32_e32 v55, v58, v72
	v_min_f32_e32 v58, v58, v72
	v_max_f32_e32 v72, v61, v60
	v_min_f32_e32 v60, v61, v60
	v_max_f32_e32 v61, v62, v56
	v_min_f32_e32 v56, v62, v56
	v_max_f32_e32 v62, v63, v53
	v_min_f32_e32 v53, v63, v53
	v_max_f32_e32 v63, v54, v59
	v_min_f32_e32 v54, v54, v59
	v_max_f32_e32 v59, v52, v57
	v_min_f32_e32 v52, v52, v57
	v_max_f32_e32 v57, v49, v48
	v_min_f32_e32 v48, v49, v48
	v_max_f32_e32 v49, v51, v50
	v_min_f32_e32 v50, v51, v50
	v_min_f32_e32 v35, v39, v64
	v_max_f32_e32 v65, v42, v44
	v_min_f32_e32 v42, v42, v44
	v_max_f32_e32 v44, v45, v43
	v_min_f32_e32 v43, v45, v43
	v_max_f32_e32 v45, v40, v36
	v_min_f32_e32 v36, v40, v36
	v_max_f32_e32 v40, v46, v47
	v_min_f32_e32 v46, v46, v47
	v_max_f32_e32 v47, v37, v38
	v_min_f32_e32 v37, v37, v38
	v_max_f32_e32 v38, v41, v33
	v_min_f32_e32 v33, v41, v33
	v_max_f32_e32 v41, v32, v34
	v_min_f32_e32 v51, v55, v72
	v_max_f32_e32 v73, v58, v60
	v_min_f32_e32 v58, v58, v60
	v_max_f32_e32 v60, v61, v59
	v_min_f32_e32 v59, v61, v59
	v_max_f32_e32 v61, v56, v52
	v_min_f32_e32 v52, v56, v52
	v_max_f32_e32 v56, v62, v63
	v_min_f32_e32 v62, v62, v63
	v_max_f32_e32 v63, v53, v54
	v_min_f32_e32 v53, v53, v54
	v_max_f32_e32 v54, v57, v49
	v_min_f32_e32 v49, v57, v49
	v_max_f32_e32 v57, v48, v50
	v_min_f32_e32 v32, v32, v34
	v_max_f32_e32 v34, v65, v35
	v_min_f32_e32 v35, v65, v35
	v_max_f32_e32 v65, v42, v38
	v_min_f32_e32 v38, v42, v38
	v_max_f32_e32 v42, v44, v40
	v_min_f32_e32 v40, v44, v40
	v_max_f32_e32 v44, v45, v46
	v_min_f32_e32 v45, v45, v46
	v_max_f32_e32 v46, v47, v43
	v_min_f32_e32 v43, v47, v43
	v_max_f32_e32 v47, v37, v36
	v_min_f32_e32 v36, v37, v36
	v_max_f32_e32 v37, v41, v33
	v_min_f32_e32 v48, v48, v50
	v_max_f32_e32 v50, v73, v51
	v_min_f32_e32 v51, v73, v51
	v_max_f32_e32 v73, v58, v54
	v_min_f32_e32 v54, v58, v54
	v_max_f32_e32 v58, v60, v56
	v_min_f32_e32 v56, v60, v56
	v_max_f32_e32 v60, v61, v62
	v_min_f32_e32 v61, v61, v62
	v_max_f32_e32 v62, v63, v59
	v_min_f32_e32 v59, v63, v59
	v_max_f32_e32 v63, v53, v52
	v_min_f32_e32 v52, v53, v52
	v_max_f32_e32 v53, v57, v49
	v_min_f32_e32 v33, v41, v33
	v_max_f32_e32 v66, v35, v40
	v_min_f32_e32 v35, v35, v40
	v_max_f32_e32 v40, v44, v46
	v_min_f32_e32 v44, v44, v46
	v_max_f32_e32 v46, v45, v43
	v_min_f32_e32 v43, v45, v43
	v_max_f32_e32 v45, v47, v37
	v_min_f32_e32 v49, v57, v49
	v_max_f32_e32 v74, v51, v56
	v_min_f32_e32 v51, v51, v56
	v_max_f32_e32 v56, v60, v62
	v_min_f32_e32 v60, v60, v62
	v_max_f32_e32 v62, v61, v59
	v_min_f32_e32 v59, v61, v59
	v_max_f32_e32 v61, v63, v53
	v_min_f32_e32 v37, v47, v37
	v_max_f32_e32 v47, v36, v33
	v_max_f32_e32 v67, v65, v35
	v_min_f32_e32 v35, v65, v35
	v_max_f32_e32 v65, v45, v38
	v_min_f32_e32 v38, v45, v38
	v_min_f32_e32 v53, v63, v53
	v_max_f32_e32 v63, v52, v49
	v_max_f32_e32 v75, v73, v51
	v_min_f32_e32 v51, v73, v51
	v_max_f32_e32 v73, v61, v54
	v_min_f32_e32 v54, v61, v54
	v_min_f32_e32 v41, v34, v42
	v_max_f32_e32 v45, v47, v37
	v_min_f32_e32 v37, v47, v37
	v_max_f32_e32 v47, v67, v40
	v_min_f32_e32 v40, v67, v40
	v_max_f32_e32 v67, v35, v44
	v_min_f32_e32 v35, v35, v44
	v_max_f32_e32 v44, v46, v65
	v_min_f32_e32 v46, v46, v65
	v_max_f32_e32 v65, v43, v38
	v_min_f32_e32 v57, v50, v58
	v_max_f32_e32 v61, v63, v53
	v_min_f32_e32 v53, v63, v53
	v_max_f32_e32 v63, v75, v56
	v_min_f32_e32 v56, v75, v56
	v_max_f32_e32 v75, v51, v60
	v_min_f32_e32 v51, v51, v60
	v_max_f32_e32 v60, v62, v73
	v_min_f32_e32 v62, v62, v73
	v_max_f32_e32 v73, v59, v54
	v_min_f32_e32 v33, v36, v33
	v_min_f32_e32 v36, v66, v41
	v_min_f32_e32 v38, v43, v38
	v_min_f32_e32 v68, v40, v67
	v_max_f32_e32 v69, v44, v35
	v_min_f32_e32 v35, v44, v35
	v_max_f32_e32 v44, v46, v65
	v_min_f32_e32 v49, v52, v49
	v_min_f32_e32 v52, v74, v57
	v_min_f32_e32 v54, v59, v54
	v_min_f32_e32 v76, v56, v75
	v_max_f32_e32 v77, v60, v51
	v_min_f32_e32 v51, v60, v51
	v_max_f32_e32 v60, v62, v73
	v_min_f32_e32 v43, v47, v36
	v_min_f32_e32 v46, v46, v65
	v_min_f32_e32 v65, v45, v38
	v_min_f32_e32 v70, v68, v69
	v_min_f32_e32 v71, v35, v44
	v_min_f32_e32 v59, v63, v52
	v_min_f32_e32 v62, v62, v73
	v_min_f32_e32 v73, v61, v54
	v_min_f32_e32 v78, v76, v77
	v_min_f32_e32 v79, v51, v60
	v_max3_f32 v39, v39, v64, v48
	v_max3_f32 v34, v34, v42, v49
	v_max3_f32 v41, v66, v41, v53
	v_max3_f32 v36, v47, v36, v73
	v_max3_f32 v42, v43, v61, v54
	v_max3_f32 v40, v40, v67, v62
	v_max3_f32 v43, v68, v69, v79
	v_max3_f32 v47, v70, v51, v60
	v_max3_f32 v35, v35, v44, v78
	v_max3_f32 v44, v71, v76, v77
	v_max3_f32 v46, v46, v56, v75
	v_max3_f32 v38, v45, v38, v59
	v_max3_f32 v45, v65, v63, v52
	v_max3_f32 v37, v37, v74, v57
	v_max3_f32 v33, v33, v50, v58
	v_max3_f32 v32, v32, v55, v72
	v_max_f32_e32 v48, v39, v35
	v_min_f32_e32 v35, v39, v35
	v_max_f32_e32 v39, v34, v44
	v_min_f32_e32 v34, v34, v44
	v_max_f32_e32 v44, v41, v46
	v_min_f32_e32 v41, v41, v46
	v_max_f32_e32 v46, v36, v38
	v_min_f32_e32 v36, v36, v38
	v_max_f32_e32 v38, v42, v45
	v_min_f32_e32 v42, v42, v45
	v_max_f32_e32 v45, v40, v37
	v_min_f32_e32 v37, v40, v37
	v_max_f32_e32 v40, v43, v33
	v_min_f32_e32 v33, v43, v33
	v_max_f32_e32 v43, v47, v32
	v_min_f32_e32 v32, v47, v32
	v_max_f32_e32 v47, v48, v38
	v_min_f32_e32 v38, v48, v38
	v_max_f32_e32 v48, v39, v45
	v_min_f32_e32 v39, v39, v45
	v_max_f32_e32 v45, v44, v40
	v_min_f32_e32 v40, v44, v40
	v_max_f32_e32 v44, v46, v43
	v_min_f32_e32 v43, v46, v43
	v_max_f32_e32 v46, v35, v42
	v_min_f32_e32 v35, v35, v42
	v_max_f32_e32 v42, v34, v37
	v_min_f32_e32 v34, v34, v37
	v_max_f32_e32 v37, v41, v33
	v_min_f32_e32 v33, v41, v33
	v_max_f32_e32 v41, v36, v32
	v_min_f32_e32 v32, v36, v32
	v_max_f32_e32 v36, v47, v45
	v_min_f32_e32 v45, v47, v45
	v_max_f32_e32 v47, v48, v44
	v_min_f32_e32 v44, v48, v44
	v_max_f32_e32 v48, v38, v40
	v_min_f32_e32 v40, v38, v40
	v_max_f32_e32 v38, v39, v43
	v_min_f32_e32 v39, v39, v43
	v_max_f32_e32 v43, v46, v37
	v_min_f32_e32 v46, v46, v37
	v_max_f32_e32 v51, v35, v33
	v_min_f32_e32 v52, v35, v33
	v_max_f32_e32 v53, v34, v32
	v_min_f32_e32 v54, v34, v32
	v_max_f32_e32 v32, v36, v47
	v_min_f32_e32 v33, v36, v47
	v_max_f32_e32 v36, v48, v38
	v_min_f32_e32 v37, v48, v38
	v_lshlrev_b32_e32 v48, 2, v142
	v_and_b32_e32 v48, 0x17c, v48
	v_or3_b32 v48, v130, v48, v118
	v_max_f32_e32 v49, v42, v41
	v_lshlrev_b32_e32 v48, 6, v48
	v_min_f32_e32 v50, v42, v41
	v_max_f32_e32 v34, v45, v44
	v_min_f32_e32 v35, v45, v44
	v_max_f32_e32 v38, v40, v39
	v_min_f32_e32 v39, v40, v39
	v_max_f32_e32 v40, v43, v49
	v_min_f32_e32 v41, v43, v49
	v_add_u32_e32 v49, v143, v48
	v_max_f32_e32 v42, v46, v50
	v_min_f32_e32 v43, v46, v50
	v_max_f32_e32 v44, v51, v53
	v_min_f32_e32 v45, v51, v53
	v_max_f32_e32 v46, v52, v54
	v_min_f32_e32 v47, v52, v54
	v_bfe_u32 v240, v49, 8, 4
	v_lshlrev_b32_e32 v240, 4, v240
	v_xor_b32_e32 v240, v49, v240
	ds_write_b128 v240, v[32:35]
	v_xor_b32_e32 v241, 16, v240
	ds_write_b128 v241, v[36:39]
	v_xor_b32_e32 v241, 32, v240
	ds_write_b128 v241, v[40:43]
	v_xor_b32_e32 v241, 48, v240
	ds_write_b128 v241, v[44:47]
	v_and_b32_e32 v16, s39, v16
	v_and_b32_e32 v17, s39, v17
	v_and_b32_e32 v18, s39, v18
	v_and_b32_e32 v19, s39, v19
	v_and_b32_e32 v20, s39, v20
	v_and_b32_e32 v21, s39, v21
	v_and_b32_e32 v22, s39, v22
	v_and_b32_e32 v23, s39, v23
	v_and_b32_e32 v24, s39, v24
	v_and_b32_e32 v25, s39, v25
	v_and_b32_e32 v26, s39, v26
	v_and_b32_e32 v27, s39, v27
	v_and_b32_e32 v28, s39, v28
	v_and_b32_e32 v29, s39, v29
	v_and_b32_e32 v30, s39, v30
	v_and_b32_e32 v31, s39, v31
	v_and_or_b32 v0, v0, s39, v119
	v_and_or_b32 v1, v1, s39, v120
	v_and_or_b32 v2, v2, s39, v121
	v_and_or_b32 v3, v3, s39, v122
	v_and_or_b32 v4, v4, s39, v123
	v_and_or_b32 v5, v5, s39, v124
	v_and_or_b32 v6, v6, s39, v125
	v_and_or_b32 v7, v7, s39, v126
	v_and_or_b32 v8, v8, s39, v127
	v_and_or_b32 v9, v9, s39, v128
	v_and_or_b32 v10, v10, s39, v96
	v_and_or_b32 v11, v11, s39, v97
	v_and_or_b32 v12, v12, s39, v98
	v_and_or_b32 v13, v13, s39, v92
	v_and_or_b32 v14, v14, s39, v88
	v_and_or_b32 v15, v15, s39, v84
	v_or3_b32 v16, v117, v16, v119
	v_or3_b32 v0, v0, v117, 32
	v_or3_b32 v17, v117, v17, v120
	v_or3_b32 v1, v1, v117, 32
	v_or3_b32 v18, v117, v18, v121
	v_or3_b32 v2, v2, v117, 32
	v_or3_b32 v19, v117, v19, v122
	v_or3_b32 v3, v3, v117, 32
	v_or3_b32 v20, v117, v20, v123
	v_or3_b32 v4, v4, v117, 32
	v_or3_b32 v21, v117, v21, v124
	v_or3_b32 v5, v5, v117, 32
	v_or3_b32 v22, v117, v22, v125
	v_or3_b32 v6, v6, v117, 32
	v_or3_b32 v23, v117, v23, v126
	v_or3_b32 v7, v7, v117, 32
	v_or3_b32 v24, v117, v24, v127
	v_or3_b32 v8, v8, v117, 32
	v_or3_b32 v25, v117, v25, v128
	v_or3_b32 v9, v9, v117, 32
	v_or3_b32 v26, v117, v26, v96
	v_or3_b32 v10, v10, v117, 32
	v_or3_b32 v27, v117, v27, v97
	v_or3_b32 v11, v11, v117, 32
	v_or3_b32 v28, v117, v28, v98
	v_or3_b32 v12, v12, v117, 32
	v_or3_b32 v29, v117, v29, v92
	v_or3_b32 v13, v13, v117, 32
	v_or3_b32 v30, v117, v30, v88
	v_or3_b32 v14, v14, v117, 32
	v_or3_b32 v31, v117, v31, v84
	v_or3_b32 v15, v15, v117, 32
	v_max_f32_e32 v32, v16, v29
	v_min_f32_e32 v16, v16, v29
	v_max_f32_e32 v29, v17, v28
	v_min_f32_e32 v17, v17, v28
	v_max_f32_e32 v28, v18, v31
	v_min_f32_e32 v18, v18, v31
	v_max_f32_e32 v31, v19, v30
	v_min_f32_e32 v19, v19, v30
	v_max_f32_e32 v30, v20, v24
	v_min_f32_e32 v20, v20, v24
	v_max_f32_e32 v24, v21, v22
	v_min_f32_e32 v21, v21, v22
	v_max_f32_e32 v22, v23, v27
	v_min_f32_e32 v23, v23, v27
	v_max_f32_e32 v27, v25, v26
	v_min_f32_e32 v25, v25, v26
	v_max_f32_e32 v40, v0, v13
	v_min_f32_e32 v0, v0, v13
	v_max_f32_e32 v13, v1, v12
	v_min_f32_e32 v1, v1, v12
	v_max_f32_e32 v12, v2, v15
	v_min_f32_e32 v2, v2, v15
	v_max_f32_e32 v15, v3, v14
	v_min_f32_e32 v3, v3, v14
	v_max_f32_e32 v14, v4, v8
	v_min_f32_e32 v4, v4, v8
	v_max_f32_e32 v8, v5, v6
	v_min_f32_e32 v5, v5, v6
	v_max_f32_e32 v6, v7, v11
	v_min_f32_e32 v7, v7, v11
	v_max_f32_e32 v11, v9, v10
	v_min_f32_e32 v9, v9, v10
	v_max_f32_e32 v26, v32, v24
	v_min_f32_e32 v24, v32, v24
	v_max_f32_e32 v32, v29, v22
	v_min_f32_e32 v22, v29, v22
	v_max_f32_e32 v29, v28, v27
	v_min_f32_e32 v27, v28, v27
	v_max_f32_e32 v28, v31, v30
	v_min_f32_e32 v30, v31, v30
	v_max_f32_e32 v31, v21, v16
	v_min_f32_e32 v16, v21, v16
	v_max_f32_e32 v21, v20, v19
	v_min_f32_e32 v19, v20, v19
	v_max_f32_e32 v20, v25, v18
	v_min_f32_e32 v18, v25, v18
	v_max_f32_e32 v25, v23, v17
	v_min_f32_e32 v17, v23, v17
	v_max_f32_e32 v10, v40, v8
	v_min_f32_e32 v8, v40, v8
	v_max_f32_e32 v40, v13, v6
	v_min_f32_e32 v6, v13, v6
	v_max_f32_e32 v13, v12, v11
	v_min_f32_e32 v11, v12, v11
	v_max_f32_e32 v12, v15, v14
	v_min_f32_e32 v14, v15, v14
	v_max_f32_e32 v15, v5, v0
	v_min_f32_e32 v0, v5, v0
	v_max_f32_e32 v5, v4, v3
	v_min_f32_e32 v3, v4, v3
	v_max_f32_e32 v4, v9, v2
	v_min_f32_e32 v2, v9, v2
	v_max_f32_e32 v9, v7, v1
	v_min_f32_e32 v1, v7, v1
	v_max_f32_e32 v23, v26, v32
	v_min_f32_e32 v26, v26, v32
	v_max_f32_e32 v32, v29, v28
	v_min_f32_e32 v28, v29, v28
	v_max_f32_e32 v29, v30, v24
	v_min_f32_e32 v24, v30, v24
	v_max_f32_e32 v30, v31, v21
	v_min_f32_e32 v21, v31, v21
	v_max_f32_e32 v31, v22, v27
	v_min_f32_e32 v22, v22, v27
	v_max_f32_e32 v27, v20, v25
	v_min_f32_e32 v20, v20, v25
	v_max_f32_e32 v25, v17, v16
	v_min_f32_e32 v16, v17, v16
	v_max_f32_e32 v17, v19, v18
	v_min_f32_e32 v18, v19, v18
	v_max_f32_e32 v7, v10, v40
	v_min_f32_e32 v10, v10, v40
	v_max_f32_e32 v40, v13, v12
	v_min_f32_e32 v12, v13, v12
	v_max_f32_e32 v13, v14, v8
	v_min_f32_e32 v8, v14, v8
	v_max_f32_e32 v14, v15, v5
	v_min_f32_e32 v5, v15, v5
	v_max_f32_e32 v15, v6, v11
	v_min_f32_e32 v6, v6, v11
	v_max_f32_e32 v11, v4, v9
	v_min_f32_e32 v4, v4, v9
	v_max_f32_e32 v9, v1, v0
	v_min_f32_e32 v0, v1, v0
	v_max_f32_e32 v1, v3, v2
	v_min_f32_e32 v2, v3, v2
	v_min_f32_e32 v19, v23, v32
	v_max_f32_e32 v33, v26, v28
	v_min_f32_e32 v26, v26, v28
	v_max_f32_e32 v28, v29, v27
	v_min_f32_e32 v27, v29, v27
	v_max_f32_e32 v29, v24, v20
	v_min_f32_e32 v20, v24, v20
	v_max_f32_e32 v24, v30, v31
	v_min_f32_e32 v30, v30, v31
	v_max_f32_e32 v31, v21, v22
	v_min_f32_e32 v21, v21, v22
	v_max_f32_e32 v22, v25, v17
	v_min_f32_e32 v17, v25, v17
	v_max_f32_e32 v25, v16, v18
	v_min_f32_e32 v3, v7, v40
	v_max_f32_e32 v41, v10, v12
	v_min_f32_e32 v10, v10, v12
	v_max_f32_e32 v12, v13, v11
	v_min_f32_e32 v11, v13, v11
	v_max_f32_e32 v13, v8, v4
	v_min_f32_e32 v4, v8, v4
	v_max_f32_e32 v8, v14, v15
	v_min_f32_e32 v14, v14, v15
	v_max_f32_e32 v15, v5, v6
	v_min_f32_e32 v5, v5, v6
	v_max_f32_e32 v6, v9, v1
	v_min_f32_e32 v1, v9, v1
	v_max_f32_e32 v9, v0, v2
	v_min_f32_e32 v16, v16, v18
	v_max_f32_e32 v18, v33, v19
	v_min_f32_e32 v19, v33, v19
	v_max_f32_e32 v33, v26, v22
	v_min_f32_e32 v22, v26, v22
	v_max_f32_e32 v26, v28, v24
	v_min_f32_e32 v24, v28, v24
	v_max_f32_e32 v28, v29, v30
	v_min_f32_e32 v29, v29, v30
	v_max_f32_e32 v30, v31, v27
	v_min_f32_e32 v27, v31, v27
	v_max_f32_e32 v31, v21, v20
	v_min_f32_e32 v20, v21, v20
	v_max_f32_e32 v21, v25, v17
	v_min_f32_e32 v0, v0, v2
	v_max_f32_e32 v2, v41, v3
	v_min_f32_e32 v3, v41, v3
	v_max_f32_e32 v41, v10, v6
	v_min_f32_e32 v6, v10, v6
	v_max_f32_e32 v10, v12, v8
	v_min_f32_e32 v8, v12, v8
	v_max_f32_e32 v12, v13, v14
	v_min_f32_e32 v13, v13, v14
	v_max_f32_e32 v14, v15, v11
	v_min_f32_e32 v11, v15, v11
	v_max_f32_e32 v15, v5, v4
	v_min_f32_e32 v4, v5, v4
	v_max_f32_e32 v5, v9, v1
	v_min_f32_e32 v17, v25, v17
	v_max_f32_e32 v34, v19, v24
	v_min_f32_e32 v19, v19, v24
	v_max_f32_e32 v24, v28, v30
	v_min_f32_e32 v28, v28, v30
	v_max_f32_e32 v30, v29, v27
	v_min_f32_e32 v27, v29, v27
	v_max_f32_e32 v29, v31, v21
	v_min_f32_e32 v1, v9, v1
	v_max_f32_e32 v42, v3, v8
	v_min_f32_e32 v3, v3, v8
	v_max_f32_e32 v8, v12, v14
	v_min_f32_e32 v12, v12, v14
	v_max_f32_e32 v14, v13, v11
	v_min_f32_e32 v11, v13, v11
	v_max_f32_e32 v13, v15, v5
	v_min_f32_e32 v21, v31, v21
	v_max_f32_e32 v31, v20, v17
	v_max_f32_e32 v35, v33, v19
	v_min_f32_e32 v19, v33, v19
	v_max_f32_e32 v33, v29, v22
	v_min_f32_e32 v22, v29, v22
	v_min_f32_e32 v5, v15, v5
	v_max_f32_e32 v15, v4, v1
	v_max_f32_e32 v43, v41, v3
	v_min_f32_e32 v3, v41, v3
	v_max_f32_e32 v41, v13, v6
	v_min_f32_e32 v6, v13, v6
	v_min_f32_e32 v25, v18, v26
	v_max_f32_e32 v29, v31, v21
	v_min_f32_e32 v21, v31, v21
	v_max_f32_e32 v31, v35, v24
	v_min_f32_e32 v24, v35, v24
	v_max_f32_e32 v35, v19, v28
	v_min_f32_e32 v19, v19, v28
	v_max_f32_e32 v28, v30, v33
	v_min_f32_e32 v30, v30, v33
	v_max_f32_e32 v33, v27, v22
	v_min_f32_e32 v9, v2, v10
	v_max_f32_e32 v13, v15, v5
	v_min_f32_e32 v5, v15, v5
	v_max_f32_e32 v15, v43, v8
	v_min_f32_e32 v8, v43, v8
	v_max_f32_e32 v43, v3, v12
	v_min_f32_e32 v3, v3, v12
	v_max_f32_e32 v12, v14, v41
	v_min_f32_e32 v14, v14, v41
	v_max_f32_e32 v41, v11, v6
	v_min_f32_e32 v17, v20, v17
	v_min_f32_e32 v20, v34, v25
	v_min_f32_e32 v22, v27, v22
	v_min_f32_e32 v36, v24, v35
	v_max_f32_e32 v37, v28, v19
	v_min_f32_e32 v19, v28, v19
	v_max_f32_e32 v28, v30, v33
	v_min_f32_e32 v1, v4, v1
	v_min_f32_e32 v4, v42, v9
	v_min_f32_e32 v6, v11, v6
	v_min_f32_e32 v44, v8, v43
	v_max_f32_e32 v45, v12, v3
	v_min_f32_e32 v3, v12, v3
	v_max_f32_e32 v12, v14, v41
	v_min_f32_e32 v27, v31, v20
	v_min_f32_e32 v30, v30, v33
	v_min_f32_e32 v33, v29, v22
	v_min_f32_e32 v38, v36, v37
	v_min_f32_e32 v39, v19, v28
	v_min_f32_e32 v11, v15, v4
	v_min_f32_e32 v14, v14, v41
	v_min_f32_e32 v41, v13, v6
	v_min_f32_e32 v46, v44, v45
	v_min_f32_e32 v47, v3, v12
	v_max3_f32 v0, v23, v32, v0
	v_max3_f32 v1, v18, v26, v1
	v_max3_f32 v5, v34, v25, v5
	v_max3_f32 v18, v31, v20, v41
	v_max3_f32 v6, v27, v13, v6
	v_max3_f32 v13, v24, v35, v14
	v_max3_f32 v14, v36, v37, v47
	v_max3_f32 v3, v38, v3, v12
	v_max3_f32 v12, v19, v28, v46
	v_max3_f32 v19, v39, v44, v45
	v_max3_f32 v8, v30, v8, v43
	v_max3_f32 v11, v29, v22, v11
	v_max3_f32 v4, v33, v15, v4
	v_max3_f32 v9, v21, v42, v9
	v_max3_f32 v2, v17, v2, v10
	v_max3_f32 v7, v16, v7, v40
	v_max_f32_e32 v10, v0, v12
	v_min_f32_e32 v0, v0, v12
	v_max_f32_e32 v12, v1, v19
	v_max_f32_e32 v15, v5, v8
	v_min_f32_e32 v5, v5, v8
	v_max_f32_e32 v8, v18, v11
	v_max_f32_e32 v16, v6, v4
	v_min_f32_e32 v4, v6, v4
	v_max_f32_e32 v6, v13, v9
	v_min_f32_e32 v9, v13, v9
	v_max_f32_e32 v13, v14, v2
	v_min_f32_e32 v2, v14, v2
	v_max_f32_e32 v14, v3, v7
	v_min_f32_e32 v1, v1, v19
	v_min_f32_e32 v11, v18, v11
	v_min_f32_e32 v3, v3, v7
	v_max_f32_e32 v7, v10, v16
	v_min_f32_e32 v10, v10, v16
	v_max_f32_e32 v16, v12, v6
	v_min_f32_e32 v6, v12, v6
	v_max_f32_e32 v12, v15, v13
	v_min_f32_e32 v13, v15, v13
	v_max_f32_e32 v15, v8, v14
	v_min_f32_e32 v8, v8, v14
	v_max_f32_e32 v14, v0, v4
	v_min_f32_e32 v0, v0, v4
	v_max_f32_e32 v4, v1, v9
	v_min_f32_e32 v1, v1, v9
	v_max_f32_e32 v9, v5, v2
	v_min_f32_e32 v2, v5, v2
	v_max_f32_e32 v5, v11, v3
	v_min_f32_e32 v3, v11, v3
	v_max_f32_e32 v11, v7, v12
	v_min_f32_e32 v7, v7, v12
	v_max_f32_e32 v12, v16, v15
	v_min_f32_e32 v15, v16, v15
	v_max_f32_e32 v16, v10, v13
	v_min_f32_e32 v10, v10, v13
	v_max_f32_e32 v13, v6, v8
	v_max_f32_e32 v17, v14, v9
	v_min_f32_e32 v14, v14, v9
	v_max_f32_e32 v9, v4, v5
	v_min_f32_e32 v18, v4, v5
	v_max_f32_e32 v4, v16, v13
	v_min_f32_e32 v5, v16, v13
	v_or_b32_e32 v16, 0x2000, v48
	v_min_f32_e32 v8, v6, v8
	v_max_f32_e32 v19, v0, v2
	v_min_f32_e32 v20, v0, v2
	v_max_f32_e32 v21, v1, v3
	v_min_f32_e32 v22, v1, v3
	v_max_f32_e32 v0, v11, v12
	v_min_f32_e32 v1, v11, v12
	v_max_f32_e32 v2, v7, v15
	v_min_f32_e32 v3, v7, v15
	v_add_u32_e32 v16, v143, v16
	v_max_f32_e32 v6, v10, v8
	v_min_f32_e32 v7, v10, v8
	v_max_f32_e32 v8, v17, v9
	v_min_f32_e32 v9, v17, v9
	v_max_f32_e32 v10, v14, v18
	v_min_f32_e32 v11, v14, v18
	v_max_f32_e32 v12, v19, v21
	v_min_f32_e32 v13, v19, v21
	v_max_f32_e32 v14, v20, v22
	v_min_f32_e32 v15, v20, v22
	v_bfe_u32 v240, v16, 8, 4
	v_lshlrev_b32_e32 v240, 4, v240
	v_xor_b32_e32 v240, v16, v240
	ds_write_b128 v240, v[0:3]
	v_xor_b32_e32 v241, 16, v240
	ds_write_b128 v241, v[4:7]
	v_xor_b32_e32 v241, 32, v240
	ds_write_b128 v241, v[8:11]
	v_xor_b32_e32 v241, 48, v240
	ds_write_b128 v241, v[12:15]
	s_waitcnt lgkmcnt(0)
	s_barrier
	s_and_saveexec_b64 s[24:25], vcc
	s_cbranch_execz .LBB0_886
	v_lshl_add_u32 v60, v142, 8, v143
	v_bfe_u32 v240, v60, 8, 4
	v_lshlrev_b32_e32 v240, 4, v240
	v_xor_b32_e32 v240, v60, v240
	ds_read_b128 v[0:3], v240
	v_xor_b32_e32 v241, 16, v240
	ds_read_b128 v[4:7], v241
	v_xor_b32_e32 v241, 32, v240
	ds_read_b128 v[8:11], v241
	v_xor_b32_e32 v241, 48, v240
	ds_read_b128 v[12:15], v241
	v_xor_b32_e32 v241, 64, v240
	ds_read_b128 v[16:19], v241
	v_xor_b32_e32 v241, 0x50, v240
	ds_read_b128 v[20:23], v241
	v_xor_b32_e32 v241, 0x80, v240
	ds_read_b128 v[24:27], v241
	v_xor_b32_e32 v241, 0x90, v240
	ds_read_b128 v[28:31], v241
	v_xor_b32_e32 v241, 0xc0, v240
	ds_read_b128 v[32:35], v241
	v_xor_b32_e32 v241, 0xd0, v240
	ds_read_b128 v[36:39], v241
	v_xor_b32_e32 v241, 0x60, v240
	ds_read_b128 v[40:43], v241
	v_xor_b32_e32 v241, 0x70, v240
	ds_read_b128 v[44:47], v241
	v_xor_b32_e32 v241, 0xa0, v240
	ds_read_b128 v[48:51], v241
	v_xor_b32_e32 v241, 0xb0, v240
	ds_read_b128 v[52:55], v241
	v_xor_b32_e32 v241, 0xe0, v240
	ds_read_b128 v[56:59], v241
	v_xor_b32_e32 v241, 0xf0, v240
	ds_read_b128 v[60:63], v241
	s_waitcnt lgkmcnt(4)
	v_max_f32_e32 v0, v0, v47
	v_max_f32_e32 v1, v1, v46
	v_max_f32_e32 v2, v2, v45
	v_max_f32_e32 v3, v3, v44
	v_max_f32_e32 v4, v4, v43
	v_max_f32_e32 v5, v5, v42
	v_max_f32_e32 v6, v6, v41
	v_max_f32_e32 v7, v7, v40
	v_max_f32_e32 v8, v8, v23
	v_max_f32_e32 v9, v9, v22
	v_max_f32_e32 v10, v10, v21
	v_max_f32_e32 v11, v11, v20
	v_max_f32_e32 v12, v12, v19
	v_max_f32_e32 v13, v13, v18
	v_max_f32_e32 v14, v14, v17
	v_max_f32_e32 v15, v15, v16
	s_waitcnt lgkmcnt(0)
	v_max_f32_e32 v24, v24, v63
	v_max_f32_e32 v25, v25, v62
	v_max_f32_e32 v26, v26, v61
	v_max_f32_e32 v27, v27, v60
	v_max_f32_e32 v28, v28, v59
	v_max_f32_e32 v29, v29, v58
	v_max_f32_e32 v30, v30, v57
	v_max_f32_e32 v31, v31, v56
	v_max_f32_e32 v39, v48, v39
	v_max_f32_e32 v38, v49, v38
	v_max_f32_e32 v37, v50, v37
	v_max_f32_e32 v36, v51, v36
	v_max_f32_e32 v35, v52, v35
	v_max_f32_e32 v34, v53, v34
	v_max_f32_e32 v33, v54, v33
	v_max_f32_e32 v32, v55, v32
	v_max_f32_e32 v16, v0, v8
	v_min_f32_e32 v0, v0, v8
	v_max_f32_e32 v8, v1, v9
	v_min_f32_e32 v1, v1, v9
	v_max_f32_e32 v9, v2, v10
	v_min_f32_e32 v2, v2, v10
	v_max_f32_e32 v10, v3, v11
	v_min_f32_e32 v3, v3, v11
	v_max_f32_e32 v11, v4, v12
	v_min_f32_e32 v4, v4, v12
	v_max_f32_e32 v12, v5, v13
	v_min_f32_e32 v5, v5, v13
	v_max_f32_e32 v13, v6, v14
	v_min_f32_e32 v6, v6, v14
	v_max_f32_e32 v14, v7, v15
	v_min_f32_e32 v7, v7, v15
	v_max_f32_e32 v40, v24, v39
	v_min_f32_e32 v24, v24, v39
	v_max_f32_e32 v39, v25, v38
	v_min_f32_e32 v25, v25, v38
	v_max_f32_e32 v38, v26, v37
	v_min_f32_e32 v26, v26, v37
	v_max_f32_e32 v37, v27, v36
	v_min_f32_e32 v27, v27, v36
	v_max_f32_e32 v36, v28, v35
	v_min_f32_e32 v28, v28, v35
	v_max_f32_e32 v35, v29, v34
	v_min_f32_e32 v29, v29, v34
	v_max_f32_e32 v34, v30, v33
	v_min_f32_e32 v30, v30, v33
	v_max_f32_e32 v33, v31, v32
	v_min_f32_e32 v31, v31, v32
	v_max_f32_e32 v15, v16, v11
	v_min_f32_e32 v11, v16, v11
	v_max_f32_e32 v16, v8, v12
	v_min_f32_e32 v8, v8, v12
	v_max_f32_e32 v12, v9, v13
	v_min_f32_e32 v9, v9, v13
	v_max_f32_e32 v13, v10, v14
	v_min_f32_e32 v10, v10, v14
	v_max_f32_e32 v14, v0, v4
	v_min_f32_e32 v0, v0, v4
	v_max_f32_e32 v4, v1, v5
	v_min_f32_e32 v1, v1, v5
	v_max_f32_e32 v5, v2, v6
	v_min_f32_e32 v2, v2, v6
	v_max_f32_e32 v6, v3, v7
	v_min_f32_e32 v3, v3, v7
	v_max_f32_e32 v32, v40, v36
	v_min_f32_e32 v36, v40, v36
	v_max_f32_e32 v40, v39, v35
	v_min_f32_e32 v35, v39, v35
	v_max_f32_e32 v39, v38, v34
	v_min_f32_e32 v34, v38, v34
	v_max_f32_e32 v38, v37, v33
	v_min_f32_e32 v33, v37, v33
	v_max_f32_e32 v37, v24, v28
	v_min_f32_e32 v24, v24, v28
	v_max_f32_e32 v28, v25, v29
	v_min_f32_e32 v25, v25, v29
	v_max_f32_e32 v29, v26, v30
	v_min_f32_e32 v26, v26, v30
	v_max_f32_e32 v30, v27, v31
	v_min_f32_e32 v27, v27, v31
	v_max_f32_e32 v7, v15, v12
	v_min_f32_e32 v12, v15, v12
	v_max_f32_e32 v15, v16, v13
	v_min_f32_e32 v13, v16, v13
	v_max_f32_e32 v16, v11, v9
	v_min_f32_e32 v9, v11, v9
	v_max_f32_e32 v11, v8, v10
	v_min_f32_e32 v8, v8, v10
	v_max_f32_e32 v10, v14, v5
	v_min_f32_e32 v5, v14, v5
	v_max_f32_e32 v14, v4, v6
	v_min_f32_e32 v4, v4, v6
	v_max_f32_e32 v6, v0, v2
	v_min_f32_e32 v0, v0, v2
	v_max_f32_e32 v2, v1, v3
	v_min_f32_e32 v1, v1, v3
	v_max_f32_e32 v31, v32, v39
	v_min_f32_e32 v32, v32, v39
	v_max_f32_e32 v39, v40, v38
	v_min_f32_e32 v38, v40, v38
	v_max_f32_e32 v40, v36, v34
	v_min_f32_e32 v34, v36, v34
	v_max_f32_e32 v36, v35, v33
	v_min_f32_e32 v33, v35, v33
	v_max_f32_e32 v35, v37, v29
	v_min_f32_e32 v29, v37, v29
	v_max_f32_e32 v37, v28, v30
	v_min_f32_e32 v28, v28, v30
	v_max_f32_e32 v30, v24, v26
	v_min_f32_e32 v24, v24, v26
	v_max_f32_e32 v26, v25, v27
	v_min_f32_e32 v25, v25, v27
	v_min_f32_e32 v3, v7, v15
	v_min_f32_e32 v17, v12, v13
	v_min_f32_e32 v18, v16, v11
	v_min_f32_e32 v19, v9, v8
	v_min_f32_e32 v20, v10, v14
	v_min_f32_e32 v21, v5, v4
	v_min_f32_e32 v22, v6, v2
	v_min_f32_e32 v23, v0, v1
	v_min_f32_e32 v27, v31, v39
	v_min_f32_e32 v41, v32, v38
	v_min_f32_e32 v42, v40, v36
	v_min_f32_e32 v43, v34, v33
	v_min_f32_e32 v44, v35, v37
	v_min_f32_e32 v45, v29, v28
	v_min_f32_e32 v46, v30, v26
	v_min_f32_e32 v47, v24, v25
	v_max3_f32 v7, v7, v15, v47
	v_max3_f32 v3, v3, v24, v25
	v_max3_f32 v12, v12, v13, v46
	v_max3_f32 v13, v17, v30, v26
	v_max3_f32 v11, v16, v11, v45
	v_max3_f32 v15, v18, v29, v28
	v_max3_f32 v8, v9, v8, v44
	v_max3_f32 v9, v19, v35, v37
	v_max3_f32 v10, v10, v14, v43
	v_max3_f32 v14, v20, v34, v33
	v_max3_f32 v4, v5, v4, v42
	v_max3_f32 v5, v21, v40, v36
	v_max3_f32 v2, v6, v2, v41
	v_max3_f32 v6, v22, v32, v38
	v_max3_f32 v0, v0, v1, v27
	v_max3_f32 v1, v23, v31, v39
	v_max_f32_e32 v16, v7, v10
	v_min_f32_e32 v7, v7, v10
	v_max_f32_e32 v10, v3, v14
	v_min_f32_e32 v3, v3, v14
	v_max_f32_e32 v14, v12, v4
	v_min_f32_e32 v4, v12, v4
	v_max_f32_e32 v12, v13, v5
	v_min_f32_e32 v5, v13, v5
	v_max_f32_e32 v13, v11, v2
	v_min_f32_e32 v2, v11, v2
	v_max_f32_e32 v11, v15, v6
	v_min_f32_e32 v6, v15, v6
	v_max_f32_e32 v15, v8, v0
	v_min_f32_e32 v0, v8, v0
	v_max_f32_e32 v8, v9, v1
	v_min_f32_e32 v1, v9, v1
	v_max_f32_e32 v9, v16, v13
	v_min_f32_e32 v13, v16, v13
	v_max_f32_e32 v16, v10, v11
	v_min_f32_e32 v10, v10, v11
	v_max_f32_e32 v11, v14, v15
	v_min_f32_e32 v14, v14, v15
	v_max_f32_e32 v15, v12, v8
	v_min_f32_e32 v8, v12, v8
	v_max_f32_e32 v12, v7, v2
	v_min_f32_e32 v2, v7, v2
	v_max_f32_e32 v7, v3, v6
	v_min_f32_e32 v3, v3, v6
	v_max_f32_e32 v6, v4, v0
	v_min_f32_e32 v0, v4, v0
	v_max_f32_e32 v4, v5, v1
	v_min_f32_e32 v1, v5, v1
	v_max_f32_e32 v5, v9, v11
	v_min_f32_e32 v9, v9, v11
	v_max_f32_e32 v11, v16, v15
	v_min_f32_e32 v15, v16, v15
	v_max_f32_e32 v16, v13, v14
	v_min_f32_e32 v13, v13, v14
	v_max_f32_e32 v14, v10, v8
	v_min_f32_e32 v8, v10, v8
	v_max_f32_e32 v10, v12, v6
	v_max_f32_e32 v17, v7, v4
	v_min_f32_e32 v18, v7, v4
	v_max_f32_e32 v19, v2, v0
	v_min_f32_e32 v20, v2, v0
	v_max_f32_e32 v21, v3, v1
	v_min_f32_e32 v22, v3, v1
	v_max_f32_e32 v0, v5, v11
	v_min_f32_e32 v1, v5, v11
	v_max_f32_e32 v4, v16, v14
	v_min_f32_e32 v5, v16, v14
	v_or_b32_e32 v16, s46, v142
	v_min_f32_e32 v12, v12, v6
	v_max_f32_e32 v2, v9, v15
	v_min_f32_e32 v3, v9, v15
	v_max_f32_e32 v6, v13, v8
	v_min_f32_e32 v7, v13, v8
	v_max_f32_e32 v8, v10, v17
	v_min_f32_e32 v9, v10, v17
	v_ashrrev_i32_e32 v17, 31, v16
	v_lshlrev_b64 v[16:17], 10, v[16:17]
	s_lshl_b32 s22, s22, 4
	v_lshl_add_u64 v[16:17], s[18:19], 0, v[16:17]
	s_ashr_i32 s23, s22, 31
	v_lshl_add_u64 v[16:17], s[22:23], 2, v[16:17]
	v_max_f32_e32 v10, v12, v18
	v_min_f32_e32 v11, v12, v18
	v_max_f32_e32 v12, v19, v21
	v_min_f32_e32 v13, v19, v21
	v_max_f32_e32 v14, v20, v22
	v_min_f32_e32 v15, v20, v22
	global_store_dwordx4 v[16:17], v[0:3], off
	global_store_dwordx4 v[16:17], v[4:7], off offset:16
	global_store_dwordx4 v[16:17], v[8:11], off offset:32
	global_store_dwordx4 v[16:17], v[12:15], off offset:48
	s_branch .LBB0_886

.LBB0_978:
	v_add_u32_e32 v141, s33, v116
	v_cmp_gt_i32_e32 vcc, s46, v141
	s_waitcnt vmcnt(0)
	ds_write_b128 v131, v[112:115]
	v_mov_b32_e32 v23, 0xff800000
	v_cndmask_b32_e32 v0, v116, v141, vcc
	v_ashrrev_i32_e32 v1, 31, v0
	v_lshlrev_b64 v[0:1], 10, v[0:1]
	v_lshl_add_u64 v[0:1], v[118:119], 0, v[0:1]
	global_load_dwordx4 v[112:115], v[0:1], off
	s_waitcnt lgkmcnt(0)
	ds_read_b32 v25, v137
	ds_read_b32 v26, v138 offset:64
	v_cmp_lt_i32_e32 vcc, s47, v141
	v_mov_b32_e32 v27, 0xff800000
	s_and_saveexec_b64 s[16:17], s[4:5]
	s_cbranch_execz .LBB0_980
	s_waitcnt lgkmcnt(0)
	v_and_b32_e32 v0, 0xffffff80, v26
	v_and_b32_e32 v1, 0xffffff80, v25
	v_add_f32_e32 v27, v0, v1
.LBB0_980:
	s_or_b64 exec, exec, s[16:17]
	ds_read_b32 v20, v137 offset:128
	ds_read_b32 v21, v138 offset:192
	v_ashrrev_i32_e32 v0, 31, v27
	v_or_b32_e32 v0, 0x80000000, v0
	v_bitop3_b32 v0, v0, s48, v27 bitop3:0x48
	v_bitop3_b32 v29, v0, 63, v124 bitop3:0x36
	ds_write_b32 v133, v29 offset:1024
	s_and_saveexec_b64 s[16:17], s[4:5]
	s_cbranch_execz .LBB0_982
	s_waitcnt lgkmcnt(1)
	v_and_b32_e32 v0, 0xffffff80, v21
	v_and_b32_e32 v1, 0xffffff80, v20
	v_add_f32_e32 v23, v0, v1
.LBB0_982:
	s_or_b64 exec, exec, s[16:17]
	ds_read_b32 v17, v137 offset:256
	ds_read_b32 v18, v138 offset:320
	v_ashrrev_i32_e32 v0, 31, v23
	v_or_b32_e32 v0, 0x80000000, v0
	v_bitop3_b32 v0, v0, s48, v23 bitop3:0x48
	v_bitop3_b32 v30, v0, 63, v124 bitop3:0x36
	v_mov_b32_e32 v16, 0xff800000
	v_mov_b32_e32 v22, 0xff800000
	ds_write_b32 v133, v30 offset:1280
	s_and_saveexec_b64 s[16:17], s[4:5]
	s_cbranch_execz .LBB0_984
	s_waitcnt lgkmcnt(1)
	v_and_b32_e32 v0, 0xffffff80, v18
	v_and_b32_e32 v1, 0xffffff80, v17
	v_add_f32_e32 v22, v0, v1
.LBB0_984:
	s_or_b64 exec, exec, s[16:17]
	ds_read_b32 v13, v137 offset:384
	ds_read_b32 v14, v138 offset:448
	v_ashrrev_i32_e32 v0, 31, v22
	v_or_b32_e32 v0, 0x80000000, v0
	v_bitop3_b32 v0, v0, s48, v22 bitop3:0x48
	v_bitop3_b32 v31, v0, 63, v124 bitop3:0x36
	ds_write_b32 v133, v31 offset:1536
	s_and_saveexec_b64 s[16:17], s[4:5]
	s_cbranch_execz .LBB0_986
	s_waitcnt lgkmcnt(1)
	v_and_b32_e32 v0, 0xffffff80, v14
	v_and_b32_e32 v1, 0xffffff80, v13
	v_add_f32_e32 v16, v0, v1
.LBB0_986:
	s_or_b64 exec, exec, s[16:17]
	ds_read_b32 v10, v137 offset:512
	ds_read_b32 v11, v138 offset:576
	v_ashrrev_i32_e32 v0, 31, v16
	v_or_b32_e32 v0, 0x80000000, v0
	v_bitop3_b32 v0, v0, s48, v16 bitop3:0x48
	v_bitop3_b32 v33, v0, 63, v124 bitop3:0x36
	v_mov_b32_e32 v9, 0xff800000
	v_mov_b32_e32 v15, 0xff800000
	ds_write_b32 v133, v33 offset:1792
	s_and_saveexec_b64 s[16:17], s[4:5]
	s_cbranch_execz .LBB0_988
	s_waitcnt lgkmcnt(1)
	v_and_b32_e32 v0, 0xffffff80, v11
	v_and_b32_e32 v1, 0xffffff80, v10
	v_add_f32_e32 v15, v0, v1
.LBB0_988:
	s_or_b64 exec, exec, s[16:17]
	ds_read_b32 v6, v137 offset:640
	ds_read_b32 v7, v138 offset:704
	v_ashrrev_i32_e32 v0, 31, v15
	v_or_b32_e32 v0, 0x80000000, v0
	v_bitop3_b32 v0, v0, s48, v15 bitop3:0x48
	v_bitop3_b32 v34, v0, 63, v124 bitop3:0x36
	ds_write_b32 v133, v34 offset:2048
	s_and_saveexec_b64 s[16:17], s[4:5]
	s_cbranch_execz .LBB0_990
	s_waitcnt lgkmcnt(1)
	v_and_b32_e32 v0, 0xffffff80, v7
	v_and_b32_e32 v1, 0xffffff80, v6
	v_add_f32_e32 v9, v0, v1
.LBB0_990:
	s_or_b64 exec, exec, s[16:17]
	ds_read_b32 v3, v137 offset:768
	ds_read_b32 v4, v138 offset:832
	v_ashrrev_i32_e32 v0, 31, v9
	v_or_b32_e32 v0, 0x80000000, v0
	v_bitop3_b32 v0, v0, s48, v9 bitop3:0x48
	v_bitop3_b32 v36, v0, 63, v124 bitop3:0x36
	v_mov_b32_e32 v2, 0xff800000
	v_mov_b32_e32 v8, 0xff800000
	ds_write_b32 v133, v36 offset:2304
	s_and_saveexec_b64 s[16:17], s[4:5]
	s_cbranch_execz .LBB0_992
	s_waitcnt lgkmcnt(1)
	v_and_b32_e32 v0, 0xffffff80, v4
	v_and_b32_e32 v1, 0xffffff80, v3
	v_add_f32_e32 v8, v0, v1
.LBB0_992:
	s_or_b64 exec, exec, s[16:17]
	ds_read_b32 v0, v137 offset:896
	ds_read_b32 v1, v138 offset:960
	v_ashrrev_i32_e32 v5, 31, v8
	v_or_b32_e32 v5, 0x80000000, v5
	v_bitop3_b32 v5, v5, s48, v8 bitop3:0x48
	v_bitop3_b32 v37, v5, 63, v124 bitop3:0x36
	ds_write_b32 v133, v37 offset:2560
	s_and_saveexec_b64 s[16:17], s[4:5]
	s_cbranch_execz .LBB0_994
	s_waitcnt lgkmcnt(1)
	v_and_b32_e32 v2, 0xffffff80, v1
	v_and_b32_e32 v5, 0xffffff80, v0
	v_add_f32_e32 v2, v2, v5
